# v5: deterministic adaLN + EpiRes epilogues (3 sites) loads-up-front, both wave groups epilogues overlapped (group 1 before its last loop barrier)
# baseline (speedup 1.0000x reference)
.LBB0_1030:
	ds_read_b128 v[148:151], v159
	ds_read_b128 v[152:155], v159 offset:1024
	ds_read_b128 v[162:165], v159 offset:2048
	ds_read_b128 v[166:169], v159 offset:3072
	s_add_u32 s20, s48, 0xffe00080
	s_addc_u32 s21, s49, -1
	s_cmpk_eq_i32 s63, 0x7c
	s_cselect_b32 s21, s17, s21
	s_cselect_b32 s20, s59, s20
	s_cselect_b32 s51, s15, s62
	s_cselect_b32 s50, s60, s61
	v_lshl_add_u64 v[190:191], s[48:49], 0, v[136:137]
	s_add_i32 m0, s37, 0xc000
	ds_read_b128 v[170:173], v160
	ds_read_b128 v[174:177], v160 offset:1024
	ds_read_b128 v[178:181], v160 offset:2048
	ds_read_b128 v[182:185], v160 offset:3072
	ds_read_b128 v[186:189], v160 offset:4096
	ds_read_b128 v[196:199], v160 offset:5120
	ds_read_b128 v[200:203], v160 offset:6144
	ds_read_b128 v[204:207], v160 offset:7168
	global_load_lds_dwordx4 v[190:191], off
	v_lshl_add_u64 v[190:191], s[48:49], 0, v[138:139]
	s_add_i32 m0, s37, 0xe000
	s_nop 0
	global_load_lds_dwordx4 v[190:191], off
	s_waitcnt lgkmcnt(8)
	s_barrier
	s_waitcnt lgkmcnt(0)
	s_setprio 1
	s_waitcnt lgkmcnt(0)
	v_mfma_f32_16x16x32_bf16 v[124:127], v[148:151], v[170:173], v[124:127]
	v_mfma_f32_16x16x32_bf16 v[120:123], v[162:165], v[170:173], v[120:123]
	v_mfma_f32_16x16x32_bf16 v[108:111], v[148:151], v[178:181], v[108:111]
	v_mfma_f32_16x16x32_bf16 v[104:107], v[162:165], v[178:181], v[104:107]
	v_mfma_f32_16x16x32_bf16 v[92:95], v[148:151], v[186:189], v[92:95]
	v_mfma_f32_16x16x32_bf16 v[88:91], v[162:165], v[186:189], v[88:91]
	v_mfma_f32_16x16x32_bf16 v[76:79], v[148:151], v[200:203], v[76:79]
	v_mfma_f32_16x16x32_bf16 v[72:75], v[162:165], v[200:203], v[72:75]
	v_mfma_f32_16x16x32_bf16 v[124:127], v[152:155], v[174:177], v[124:127]
	v_mfma_f32_16x16x32_bf16 v[120:123], v[166:169], v[174:177], v[120:123]
	v_mfma_f32_16x16x32_bf16 v[108:111], v[152:155], v[182:185], v[108:111]
	v_mfma_f32_16x16x32_bf16 v[104:107], v[166:169], v[182:185], v[104:107]
	v_mfma_f32_16x16x32_bf16 v[92:95], v[152:155], v[196:199], v[92:95]
	v_mfma_f32_16x16x32_bf16 v[88:91], v[166:169], v[196:199], v[88:91]
	v_mfma_f32_16x16x32_bf16 v[76:79], v[152:155], v[204:207], v[76:79]
	v_mfma_f32_16x16x32_bf16 v[72:75], v[166:169], v[204:207], v[72:75]
	s_setprio 0
	s_barrier
	s_add_i32 s64, s55, s23
	v_lshl_add_u64 v[190:191], s[50:51], 0, v[132:133]
	s_mov_b32 m0, s64
	ds_read_b128 v[208:211], v161
	ds_read_b128 v[212:215], v161 offset:1024
	ds_read_b128 v[216:219], v161 offset:2048
	ds_read_b128 v[220:223], v161 offset:3072
	global_load_lds_dwordx4 v[190:191], off
	v_lshl_add_u64 v[224:225], s[50:51], 0, v[128:129]
	s_add_i32 m0, s64, 0x2000
	s_nop 0
	global_load_lds_dwordx4 v[224:225], off
	s_barrier
	s_waitcnt lgkmcnt(0)
	s_setprio 1
	s_waitcnt lgkmcnt(0)
	v_mfma_f32_16x16x32_bf16 v[116:119], v[208:211], v[170:173], v[116:119]
	v_mfma_f32_16x16x32_bf16 v[112:115], v[216:219], v[170:173], v[112:115]
	v_mfma_f32_16x16x32_bf16 v[100:103], v[208:211], v[178:181], v[100:103]
	v_mfma_f32_16x16x32_bf16 v[96:99], v[216:219], v[178:181], v[96:99]
	v_mfma_f32_16x16x32_bf16 v[84:87], v[208:211], v[186:189], v[84:87]
	v_mfma_f32_16x16x32_bf16 v[80:83], v[216:219], v[186:189], v[80:83]
	v_mfma_f32_16x16x32_bf16 v[68:71], v[208:211], v[200:203], v[68:71]
	v_mfma_f32_16x16x32_bf16 v[64:67], v[216:219], v[200:203], v[64:67]
	v_mfma_f32_16x16x32_bf16 v[116:119], v[212:215], v[174:177], v[116:119]
	v_mfma_f32_16x16x32_bf16 v[112:115], v[220:223], v[174:177], v[112:115]
	v_mfma_f32_16x16x32_bf16 v[100:103], v[212:215], v[182:185], v[100:103]
	v_mfma_f32_16x16x32_bf16 v[96:99], v[220:223], v[182:185], v[96:99]
	v_mfma_f32_16x16x32_bf16 v[84:87], v[212:215], v[196:199], v[84:87]
	v_mfma_f32_16x16x32_bf16 v[80:83], v[220:223], v[196:199], v[80:83]
	v_mfma_f32_16x16x32_bf16 v[68:71], v[212:215], v[204:207], v[68:71]
	v_mfma_f32_16x16x32_bf16 v[64:67], v[220:223], v[204:207], v[64:67]
	s_setprio 0
	s_mov_b32 m0, s37
	v_lshl_add_u64 v[226:227], s[20:21], 0, v[134:135]
	s_barrier
	ds_read_b128 v[170:173], v160 offset:16384
	ds_read_b128 v[174:177], v160 offset:17408
	ds_read_b128 v[178:181], v160 offset:18432
	ds_read_b128 v[182:185], v160 offset:19456
	ds_read_b128 v[186:189], v160 offset:20480
	ds_read_b128 v[196:199], v160 offset:21504
	ds_read_b128 v[200:203], v160 offset:22528
	ds_read_b128 v[204:207], v160 offset:23552
	global_load_lds_dwordx4 v[226:227], off
	v_lshl_add_u64 v[228:229], s[20:21], 0, v[130:131]
	s_mov_b32 m0, s38
	s_nop 0
	global_load_lds_dwordx4 v[228:229], off
	s_barrier
	s_waitcnt lgkmcnt(0)
	s_setprio 1
	s_waitcnt lgkmcnt(0)
	v_mfma_f32_16x16x32_bf16 v[60:63], v[148:151], v[170:173], v[60:63]
	v_mfma_f32_16x16x32_bf16 v[56:59], v[162:165], v[170:173], v[56:59]
	v_mfma_f32_16x16x32_bf16 v[44:47], v[148:151], v[178:181], v[44:47]
	v_mfma_f32_16x16x32_bf16 v[40:43], v[162:165], v[178:181], v[40:43]
	v_mfma_f32_16x16x32_bf16 v[28:31], v[148:151], v[186:189], v[28:31]
	v_mfma_f32_16x16x32_bf16 v[24:27], v[162:165], v[186:189], v[24:27]
	v_mfma_f32_16x16x32_bf16 v[12:15], v[148:151], v[200:203], v[12:15]
	v_mfma_f32_16x16x32_bf16 v[8:11], v[162:165], v[200:203], v[8:11]
	v_mfma_f32_16x16x32_bf16 v[60:63], v[152:155], v[174:177], v[60:63]
	v_mfma_f32_16x16x32_bf16 v[56:59], v[166:169], v[174:177], v[56:59]
	v_mfma_f32_16x16x32_bf16 v[44:47], v[152:155], v[182:185], v[44:47]
	v_mfma_f32_16x16x32_bf16 v[40:43], v[166:169], v[182:185], v[40:43]
	v_mfma_f32_16x16x32_bf16 v[28:31], v[152:155], v[196:199], v[28:31]
	v_mfma_f32_16x16x32_bf16 v[24:27], v[166:169], v[196:199], v[24:27]
	v_mfma_f32_16x16x32_bf16 v[12:15], v[152:155], v[204:207], v[12:15]
	v_mfma_f32_16x16x32_bf16 v[8:11], v[166:169], v[204:207], v[8:11]
	s_setprio 0
	s_barrier
	s_add_u32 s64, s50, 0x200000
	s_addc_u32 s65, s51, 0
	s_add_i32 s66, s57, s23
	v_lshl_add_u64 v[148:149], s[64:65], 0, v[132:133]
	s_mov_b32 m0, s66
	s_nop 0
	global_load_lds_dwordx4 v[148:149], off
	v_lshl_add_u64 v[148:149], s[64:65], 0, v[128:129]
	s_add_i32 m0, s66, 0x2000
	s_nop 0
	global_load_lds_dwordx4 v[148:149], off
	s_waitcnt vmcnt(6)
	s_barrier
	s_setprio 1
	v_mfma_f32_16x16x32_bf16 v[52:55], v[208:211], v[170:173], v[52:55]
	v_mfma_f32_16x16x32_bf16 v[48:51], v[216:219], v[170:173], v[48:51]
	v_mfma_f32_16x16x32_bf16 v[36:39], v[208:211], v[178:181], v[36:39]
	v_mfma_f32_16x16x32_bf16 v[32:35], v[216:219], v[178:181], v[32:35]
	v_mfma_f32_16x16x32_bf16 v[20:23], v[208:211], v[186:189], v[20:23]
	v_mfma_f32_16x16x32_bf16 v[16:19], v[216:219], v[186:189], v[16:19]
	v_mfma_f32_16x16x32_bf16 v[4:7], v[208:211], v[200:203], v[4:7]
	v_mfma_f32_16x16x32_bf16 v[0:3], v[216:219], v[200:203], v[0:3]
	v_mfma_f32_16x16x32_bf16 v[52:55], v[212:215], v[174:177], v[52:55]
	v_mfma_f32_16x16x32_bf16 v[48:51], v[220:223], v[174:177], v[48:51]
	v_mfma_f32_16x16x32_bf16 v[36:39], v[212:215], v[182:185], v[36:39]
	v_mfma_f32_16x16x32_bf16 v[32:35], v[220:223], v[182:185], v[32:35]
	v_mfma_f32_16x16x32_bf16 v[20:23], v[212:215], v[196:199], v[20:23]
	v_mfma_f32_16x16x32_bf16 v[16:19], v[220:223], v[196:199], v[16:19]
	v_mfma_f32_16x16x32_bf16 v[4:7], v[212:215], v[204:207], v[4:7]
	v_mfma_f32_16x16x32_bf16 v[0:3], v[220:223], v[204:207], v[0:3]
	s_setprio 0
	s_add_i32 s64, 0, 0x18000
	v_add_u32_e32 v166, s64, v156
	s_barrier
	ds_read_b128 v[148:151], v166
	ds_read_b128 v[152:155], v166 offset:1024
	ds_read_b128 v[162:165], v166 offset:2048
	ds_read_b128 v[166:169], v166 offset:3072
	s_add_u32 s20, s20, 0x200000
	s_addc_u32 s21, s21, 0
	s_mov_b32 m0, s39
	v_lshl_add_u64 v[208:209], s[20:21], 0, v[134:135]
	ds_read_b128 v[170:173], v160 offset:32768
	ds_read_b128 v[174:177], v160 offset:33792
	ds_read_b128 v[178:181], v160 offset:34816
	ds_read_b128 v[182:185], v160 offset:35840
	ds_read_b128 v[186:189], v160 offset:36864
	ds_read_b128 v[196:199], v160 offset:37888
	ds_read_b128 v[200:203], v160 offset:38912
	ds_read_b128 v[204:207], v160 offset:39936
	global_load_lds_dwordx4 v[208:209], off
	v_lshl_add_u64 v[208:209], s[20:21], 0, v[130:131]
	s_mov_b32 m0, s47
	s_nop 0
	global_load_lds_dwordx4 v[208:209], off
	s_waitcnt lgkmcnt(8)
	s_barrier
	s_waitcnt lgkmcnt(0)
	s_setprio 1
	s_waitcnt lgkmcnt(0)
	v_mfma_f32_16x16x32_bf16 v[124:127], v[148:151], v[170:173], v[124:127]
	v_mfma_f32_16x16x32_bf16 v[120:123], v[162:165], v[170:173], v[120:123]
	v_mfma_f32_16x16x32_bf16 v[108:111], v[148:151], v[178:181], v[108:111]
	v_mfma_f32_16x16x32_bf16 v[104:107], v[162:165], v[178:181], v[104:107]
	v_mfma_f32_16x16x32_bf16 v[92:95], v[148:151], v[186:189], v[92:95]
	v_mfma_f32_16x16x32_bf16 v[88:91], v[162:165], v[186:189], v[88:91]
	v_mfma_f32_16x16x32_bf16 v[76:79], v[148:151], v[200:203], v[76:79]
	v_mfma_f32_16x16x32_bf16 v[72:75], v[162:165], v[200:203], v[72:75]
	v_mfma_f32_16x16x32_bf16 v[124:127], v[152:155], v[174:177], v[124:127]
	v_mfma_f32_16x16x32_bf16 v[120:123], v[166:169], v[174:177], v[120:123]
	v_mfma_f32_16x16x32_bf16 v[108:111], v[152:155], v[182:185], v[108:111]
	v_mfma_f32_16x16x32_bf16 v[104:107], v[166:169], v[182:185], v[104:107]
	v_mfma_f32_16x16x32_bf16 v[92:95], v[152:155], v[196:199], v[92:95]
	v_mfma_f32_16x16x32_bf16 v[88:91], v[166:169], v[196:199], v[88:91]
	v_mfma_f32_16x16x32_bf16 v[76:79], v[152:155], v[204:207], v[76:79]
	v_mfma_f32_16x16x32_bf16 v[72:75], v[166:169], v[204:207], v[72:75]
	s_setprio 0
	s_barrier
	s_add_i32 s65, 0, 0x1c000
	s_add_i32 s20, s64, s23
	v_add_u32_e32 v195, s65, v156
	v_lshl_add_u64 v[190:191], v[190:191], 0, s[10:11]
	s_mov_b32 m0, s20
	ds_read_b128 v[208:211], v195
	ds_read_b128 v[212:215], v195 offset:1024
	ds_read_b128 v[216:219], v195 offset:2048
	ds_read_b128 v[220:223], v195 offset:3072
	global_load_lds_dwordx4 v[190:191], off
	v_lshl_add_u64 v[190:191], v[224:225], 0, s[10:11]
	s_add_i32 m0, s20, 0x2000
	s_nop 0
	global_load_lds_dwordx4 v[190:191], off
	s_barrier
	s_waitcnt lgkmcnt(0)
	s_setprio 1
	s_waitcnt lgkmcnt(0)
	v_mfma_f32_16x16x32_bf16 v[116:119], v[208:211], v[170:173], v[116:119]
	v_mfma_f32_16x16x32_bf16 v[112:115], v[216:219], v[170:173], v[112:115]
	v_mfma_f32_16x16x32_bf16 v[100:103], v[208:211], v[178:181], v[100:103]
	v_mfma_f32_16x16x32_bf16 v[96:99], v[216:219], v[178:181], v[96:99]
	v_mfma_f32_16x16x32_bf16 v[84:87], v[208:211], v[186:189], v[84:87]
	v_mfma_f32_16x16x32_bf16 v[80:83], v[216:219], v[186:189], v[80:83]
	v_mfma_f32_16x16x32_bf16 v[68:71], v[208:211], v[200:203], v[68:71]
	v_mfma_f32_16x16x32_bf16 v[64:67], v[216:219], v[200:203], v[64:67]
	v_mfma_f32_16x16x32_bf16 v[116:119], v[212:215], v[174:177], v[116:119]
	v_mfma_f32_16x16x32_bf16 v[112:115], v[220:223], v[174:177], v[112:115]
	v_mfma_f32_16x16x32_bf16 v[100:103], v[212:215], v[182:185], v[100:103]
	v_mfma_f32_16x16x32_bf16 v[96:99], v[220:223], v[182:185], v[96:99]
	v_mfma_f32_16x16x32_bf16 v[84:87], v[212:215], v[196:199], v[84:87]
	v_mfma_f32_16x16x32_bf16 v[80:83], v[220:223], v[196:199], v[80:83]
	v_mfma_f32_16x16x32_bf16 v[68:71], v[212:215], v[204:207], v[68:71]
	v_mfma_f32_16x16x32_bf16 v[64:67], v[220:223], v[204:207], v[64:67]
	s_setprio 0
	s_mov_b32 m0, s34
	v_lshl_add_u64 v[190:191], v[226:227], 0, s[10:11]
	s_barrier
	ds_read_b128 v[170:173], v160 offset:49152
	ds_read_b128 v[174:177], v160 offset:50176
	ds_read_b128 v[178:181], v160 offset:51200
	ds_read_b128 v[182:185], v160 offset:52224
	ds_read_b128 v[186:189], v160 offset:53248
	ds_read_b128 v[196:199], v160 offset:54272
	ds_read_b128 v[200:203], v160 offset:55296
	ds_read_b128 v[204:207], v160 offset:56320
	global_load_lds_dwordx4 v[190:191], off
	v_lshl_add_u64 v[190:191], v[228:229], 0, s[10:11]
	s_mov_b32 m0, s35
	s_nop 0
	global_load_lds_dwordx4 v[190:191], off
	s_barrier
	s_waitcnt lgkmcnt(0)
	s_setprio 1
	s_waitcnt lgkmcnt(0)
	v_mfma_f32_16x16x32_bf16 v[60:63], v[148:151], v[170:173], v[60:63]
	v_mfma_f32_16x16x32_bf16 v[56:59], v[162:165], v[170:173], v[56:59]
	v_mfma_f32_16x16x32_bf16 v[44:47], v[148:151], v[178:181], v[44:47]
	v_mfma_f32_16x16x32_bf16 v[40:43], v[162:165], v[178:181], v[40:43]
	v_mfma_f32_16x16x32_bf16 v[28:31], v[148:151], v[186:189], v[28:31]
	v_mfma_f32_16x16x32_bf16 v[24:27], v[162:165], v[186:189], v[24:27]
	v_mfma_f32_16x16x32_bf16 v[12:15], v[148:151], v[200:203], v[12:15]
	v_mfma_f32_16x16x32_bf16 v[8:11], v[162:165], v[200:203], v[8:11]
	v_mfma_f32_16x16x32_bf16 v[60:63], v[152:155], v[174:177], v[60:63]
	v_mfma_f32_16x16x32_bf16 v[56:59], v[166:169], v[174:177], v[56:59]
	v_mfma_f32_16x16x32_bf16 v[44:47], v[152:155], v[182:185], v[44:47]
	v_mfma_f32_16x16x32_bf16 v[40:43], v[166:169], v[182:185], v[40:43]
	v_mfma_f32_16x16x32_bf16 v[28:31], v[152:155], v[196:199], v[28:31]
	v_mfma_f32_16x16x32_bf16 v[24:27], v[166:169], v[196:199], v[24:27]
	v_mfma_f32_16x16x32_bf16 v[12:15], v[152:155], v[204:207], v[12:15]
	v_mfma_f32_16x16x32_bf16 v[8:11], v[166:169], v[204:207], v[8:11]
	s_setprio 0
	s_barrier
	s_add_u32 s20, s50, 0x200080
	s_addc_u32 s21, s51, 0
	s_add_i32 s50, s65, s23
	v_lshl_add_u64 v[148:149], s[20:21], 0, v[132:133]
	s_mov_b32 m0, s50
	s_nop 0
	global_load_lds_dwordx4 v[148:149], off
	v_lshl_add_u64 v[148:149], s[20:21], 0, v[128:129]
	s_add_i32 m0, s50, 0x2000
	s_nop 0
	global_load_lds_dwordx4 v[148:149], off
	s_waitcnt vmcnt(6)
	s_barrier
	s_setprio 1
	v_mfma_f32_16x16x32_bf16 v[52:55], v[208:211], v[170:173], v[52:55]
	v_mfma_f32_16x16x32_bf16 v[48:51], v[216:219], v[170:173], v[48:51]
	v_mfma_f32_16x16x32_bf16 v[36:39], v[208:211], v[178:181], v[36:39]
	v_mfma_f32_16x16x32_bf16 v[32:35], v[216:219], v[178:181], v[32:35]
	v_mfma_f32_16x16x32_bf16 v[20:23], v[208:211], v[186:189], v[20:23]
	v_mfma_f32_16x16x32_bf16 v[16:19], v[216:219], v[186:189], v[16:19]
	v_mfma_f32_16x16x32_bf16 v[4:7], v[208:211], v[200:203], v[4:7]
	v_mfma_f32_16x16x32_bf16 v[0:3], v[216:219], v[200:203], v[0:3]
	v_mfma_f32_16x16x32_bf16 v[52:55], v[212:215], v[174:177], v[52:55]
	v_mfma_f32_16x16x32_bf16 v[48:51], v[220:223], v[174:177], v[48:51]
	v_mfma_f32_16x16x32_bf16 v[36:39], v[212:215], v[182:185], v[36:39]
	v_mfma_f32_16x16x32_bf16 v[32:35], v[220:223], v[182:185], v[32:35]
	v_mfma_f32_16x16x32_bf16 v[20:23], v[212:215], v[196:199], v[20:23]
	v_mfma_f32_16x16x32_bf16 v[16:19], v[220:223], v[196:199], v[16:19]
	v_mfma_f32_16x16x32_bf16 v[4:7], v[212:215], v[204:207], v[4:7]
	v_mfma_f32_16x16x32_bf16 v[0:3], v[220:223], v[204:207], v[0:3]
	s_setprio 0
	s_add_i32 s63, s63, 2
	s_add_u32 s48, s48, 0x100
	s_addc_u32 s49, s49, 0
	s_add_u32 s61, s61, 0x100
	s_addc_u32 s62, s62, 0
	s_cmpk_gt_u32 s63, 0x7d
	s_cbranch_scc0 .Lepi_nl_mlpout0
	s_cmp_lg_u32 s53, 64
	s_cbranch_scc1 .Lepi_nl_mlpout0
	s_lshl_b32 s15, s46, 8
	s_add_i32 s15, s15, s53
	v_or_b32_e32 v154, s15, v147
	s_add_i32 s17, s15, 0xffffe000
	v_lshl_or_b32 v150, s33, 8, v158
	s_lshr_b32 s17, s17, 12
	v_lshlrev_b32_e32 v148, 12, v154
	s_add_i32 s17, s17, 1
	s_cmp_gt_i32 s15, s58
	s_cselect_b32 s17, s17, 0
	s_mul_i32 s17, s17, s56
	v_lshl_add_u32 v148, v150, 1, v148
	s_add_u32 s20, s8, s17
	s_addc_u32 s21, s9, 0
	v_lshlrev_b32_e32 v149, 2, v150
	s_nop 0
	global_load_dwordx4 v[196:199], v149, s[20:21]
	global_load_dwordx4 v[200:203], v149, s[20:21] offset:16
	global_load_dwordx4 v[204:207], v149, s[20:21] offset:512
	global_load_dwordx4 v[208:211], v149, s[20:21] offset:528
	global_load_dwordx4 v[212:215], v148, s[74:75]
	global_load_dwordx4 v[216:219], v148, s[74:75] offset:256
	v_add_u32_e32 v151, 0x10000, v148
	global_load_dwordx4 v[220:223], v151, s[74:75]
	global_load_dwordx4 v[224:227], v151, s[74:75] offset:256
	v_add_u32_e32 v151, 0x20000, v148
	global_load_dwordx4 v[164:167], v151, s[74:75]
	global_load_dwordx4 v[168:171], v151, s[74:75] offset:256
	v_add_u32_e32 v151, 0x30000, v148
	global_load_dwordx4 v[172:175], v151, s[74:75]
	global_load_dwordx4 v[176:179], v151, s[74:75] offset:256
	s_waitcnt vmcnt(0)
	v_lshlrev_b32_e32 v180, 16, v212
	v_and_b32_e32 v181, 0xffff0000, v212
	v_lshlrev_b32_e32 v182, 16, v213
	v_and_b32_e32 v183, 0xffff0000, v213
	v_lshlrev_b32_e32 v184, 16, v214
	v_and_b32_e32 v185, 0xffff0000, v214
	v_lshlrev_b32_e32 v186, 16, v215
	v_and_b32_e32 v187, 0xffff0000, v215
	v_pk_fma_f32 v[124:125], v[124:125], v[196:197], v[180:181]
	v_pk_fma_f32 v[126:127], v[126:127], v[198:199], v[182:183]
	v_pk_fma_f32 v[120:121], v[120:121], v[200:201], v[184:185]
	v_pk_fma_f32 v[122:123], v[122:123], v[202:203], v[186:187]
	v_cvt_pk_bf16_f32 v123, v122, v123
	v_cvt_pk_bf16_f32 v122, v120, v121
	v_cvt_pk_bf16_f32 v121, v126, v127
	v_cvt_pk_bf16_f32 v120, v124, v125
	global_store_dwordx4 v148, v[120:123], s[74:75]
	v_lshlrev_b32_e32 v180, 16, v216
	v_and_b32_e32 v181, 0xffff0000, v216
	v_lshlrev_b32_e32 v182, 16, v217
	v_and_b32_e32 v183, 0xffff0000, v217
	v_lshlrev_b32_e32 v184, 16, v218
	v_and_b32_e32 v185, 0xffff0000, v218
	v_lshlrev_b32_e32 v186, 16, v219
	v_and_b32_e32 v187, 0xffff0000, v219
	v_pk_fma_f32 v[116:117], v[116:117], v[204:205], v[180:181]
	v_pk_fma_f32 v[118:119], v[118:119], v[206:207], v[182:183]
	v_pk_fma_f32 v[112:113], v[112:113], v[208:209], v[184:185]
	v_pk_fma_f32 v[114:115], v[114:115], v[210:211], v[186:187]
	v_cvt_pk_bf16_f32 v115, v114, v115
	v_cvt_pk_bf16_f32 v114, v112, v113
	v_cvt_pk_bf16_f32 v113, v118, v119
	v_cvt_pk_bf16_f32 v112, v116, v117
	global_store_dwordx4 v148, v[112:115], s[74:75] offset:256
	v_lshlrev_b32_e32 v180, 16, v220
	v_and_b32_e32 v181, 0xffff0000, v220
	v_lshlrev_b32_e32 v182, 16, v221
	v_and_b32_e32 v183, 0xffff0000, v221
	v_lshlrev_b32_e32 v184, 16, v222
	v_and_b32_e32 v185, 0xffff0000, v222
	v_lshlrev_b32_e32 v186, 16, v223
	v_and_b32_e32 v187, 0xffff0000, v223
	v_pk_fma_f32 v[108:109], v[108:109], v[196:197], v[180:181]
	v_pk_fma_f32 v[110:111], v[110:111], v[198:199], v[182:183]
	v_pk_fma_f32 v[104:105], v[104:105], v[200:201], v[184:185]
	v_pk_fma_f32 v[106:107], v[106:107], v[202:203], v[186:187]
	v_cvt_pk_bf16_f32 v107, v106, v107
	v_cvt_pk_bf16_f32 v106, v104, v105
	v_cvt_pk_bf16_f32 v105, v110, v111
	v_cvt_pk_bf16_f32 v104, v108, v109
	v_add_u32_e32 v151, 0x10000, v148
	global_store_dwordx4 v151, v[104:107], s[74:75]
	v_lshlrev_b32_e32 v180, 16, v224
	v_and_b32_e32 v181, 0xffff0000, v224
	v_lshlrev_b32_e32 v182, 16, v225
	v_and_b32_e32 v183, 0xffff0000, v225
	v_lshlrev_b32_e32 v184, 16, v226
	v_and_b32_e32 v185, 0xffff0000, v226
	v_lshlrev_b32_e32 v186, 16, v227
	v_and_b32_e32 v187, 0xffff0000, v227
	v_pk_fma_f32 v[100:101], v[100:101], v[204:205], v[180:181]
	v_pk_fma_f32 v[102:103], v[102:103], v[206:207], v[182:183]
	v_pk_fma_f32 v[96:97], v[96:97], v[208:209], v[184:185]
	v_pk_fma_f32 v[98:99], v[98:99], v[210:211], v[186:187]
	v_cvt_pk_bf16_f32 v99, v98, v99
	v_cvt_pk_bf16_f32 v98, v96, v97
	v_cvt_pk_bf16_f32 v97, v102, v103
	v_cvt_pk_bf16_f32 v96, v100, v101
	v_add_u32_e32 v151, 0x10000, v148
	global_store_dwordx4 v151, v[96:99], s[74:75] offset:256
	v_add_u32_e32 v151, 0x80000, v148
	global_load_dwordx4 v[212:215], v151, s[74:75]
	global_load_dwordx4 v[216:219], v151, s[74:75] offset:256
	v_add_u32_e32 v151, 0x90000, v148
	global_load_dwordx4 v[220:223], v151, s[74:75]
	global_load_dwordx4 v[224:227], v151, s[74:75] offset:256
	v_lshlrev_b32_e32 v180, 16, v164
	v_and_b32_e32 v181, 0xffff0000, v164
	v_lshlrev_b32_e32 v182, 16, v165
	v_and_b32_e32 v183, 0xffff0000, v165
	v_lshlrev_b32_e32 v184, 16, v166
	v_and_b32_e32 v185, 0xffff0000, v166
	v_lshlrev_b32_e32 v186, 16, v167
	v_and_b32_e32 v187, 0xffff0000, v167
	v_pk_fma_f32 v[92:93], v[92:93], v[196:197], v[180:181]
	v_pk_fma_f32 v[94:95], v[94:95], v[198:199], v[182:183]
	v_pk_fma_f32 v[88:89], v[88:89], v[200:201], v[184:185]
	v_pk_fma_f32 v[90:91], v[90:91], v[202:203], v[186:187]
	v_cvt_pk_bf16_f32 v91, v90, v91
	v_cvt_pk_bf16_f32 v90, v88, v89
	v_cvt_pk_bf16_f32 v89, v94, v95
	v_cvt_pk_bf16_f32 v88, v92, v93
	v_add_u32_e32 v151, 0x20000, v148
	global_store_dwordx4 v151, v[88:91], s[74:75]
	v_lshlrev_b32_e32 v180, 16, v168
	v_and_b32_e32 v181, 0xffff0000, v168
	v_lshlrev_b32_e32 v182, 16, v169
	v_and_b32_e32 v183, 0xffff0000, v169
	v_lshlrev_b32_e32 v184, 16, v170
	v_and_b32_e32 v185, 0xffff0000, v170
	v_lshlrev_b32_e32 v186, 16, v171
	v_and_b32_e32 v187, 0xffff0000, v171
	v_pk_fma_f32 v[84:85], v[84:85], v[204:205], v[180:181]
	v_pk_fma_f32 v[86:87], v[86:87], v[206:207], v[182:183]
	v_pk_fma_f32 v[80:81], v[80:81], v[208:209], v[184:185]
	v_pk_fma_f32 v[82:83], v[82:83], v[210:211], v[186:187]
	v_cvt_pk_bf16_f32 v83, v82, v83
	v_cvt_pk_bf16_f32 v82, v80, v81
	v_cvt_pk_bf16_f32 v81, v86, v87
	v_cvt_pk_bf16_f32 v80, v84, v85
	v_add_u32_e32 v151, 0x20000, v148
	global_store_dwordx4 v151, v[80:83], s[74:75] offset:256
	v_lshlrev_b32_e32 v180, 16, v172
	v_and_b32_e32 v181, 0xffff0000, v172
	v_lshlrev_b32_e32 v182, 16, v173
	v_and_b32_e32 v183, 0xffff0000, v173
	v_lshlrev_b32_e32 v184, 16, v174
	v_and_b32_e32 v185, 0xffff0000, v174
	v_lshlrev_b32_e32 v186, 16, v175
	v_and_b32_e32 v187, 0xffff0000, v175
	v_pk_fma_f32 v[76:77], v[76:77], v[196:197], v[180:181]
	v_pk_fma_f32 v[78:79], v[78:79], v[198:199], v[182:183]
	v_pk_fma_f32 v[72:73], v[72:73], v[200:201], v[184:185]
	v_pk_fma_f32 v[74:75], v[74:75], v[202:203], v[186:187]
	v_cvt_pk_bf16_f32 v75, v74, v75
	v_cvt_pk_bf16_f32 v74, v72, v73
	v_cvt_pk_bf16_f32 v73, v78, v79
	v_cvt_pk_bf16_f32 v72, v76, v77
	v_add_u32_e32 v151, 0x30000, v148
	global_store_dwordx4 v151, v[72:75], s[74:75]
	v_lshlrev_b32_e32 v180, 16, v176
	v_and_b32_e32 v181, 0xffff0000, v176
	v_lshlrev_b32_e32 v182, 16, v177
	v_and_b32_e32 v183, 0xffff0000, v177
	v_lshlrev_b32_e32 v184, 16, v178
	v_and_b32_e32 v185, 0xffff0000, v178
	v_lshlrev_b32_e32 v186, 16, v179
	v_and_b32_e32 v187, 0xffff0000, v179
	v_pk_fma_f32 v[68:69], v[68:69], v[204:205], v[180:181]
	v_pk_fma_f32 v[70:71], v[70:71], v[206:207], v[182:183]
	v_pk_fma_f32 v[64:65], v[64:65], v[208:209], v[184:185]
	v_pk_fma_f32 v[66:67], v[66:67], v[210:211], v[186:187]
	v_cvt_pk_bf16_f32 v67, v66, v67
	v_cvt_pk_bf16_f32 v66, v64, v65
	v_cvt_pk_bf16_f32 v65, v70, v71
	v_cvt_pk_bf16_f32 v64, v68, v69
	v_add_u32_e32 v151, 0x30000, v148
	global_store_dwordx4 v151, v[64:67], s[74:75] offset:256
	v_add_u32_e32 v151, 0xa0000, v148
	global_load_dwordx4 v[164:167], v151, s[74:75]
	global_load_dwordx4 v[168:171], v151, s[74:75] offset:256
	v_add_u32_e32 v151, 0xb0000, v148
	global_load_dwordx4 v[172:175], v151, s[74:75]
	global_load_dwordx4 v[176:179], v151, s[74:75] offset:256
	s_waitcnt vmcnt(0)
	v_lshlrev_b32_e32 v180, 16, v212
	v_and_b32_e32 v181, 0xffff0000, v212
	v_lshlrev_b32_e32 v182, 16, v213
	v_and_b32_e32 v183, 0xffff0000, v213
	v_lshlrev_b32_e32 v184, 16, v214
	v_and_b32_e32 v185, 0xffff0000, v214
	v_lshlrev_b32_e32 v186, 16, v215
	v_and_b32_e32 v187, 0xffff0000, v215
	v_pk_fma_f32 v[60:61], v[60:61], v[196:197], v[180:181]
	v_pk_fma_f32 v[62:63], v[62:63], v[198:199], v[182:183]
	v_pk_fma_f32 v[56:57], v[56:57], v[200:201], v[184:185]
	v_pk_fma_f32 v[58:59], v[58:59], v[202:203], v[186:187]
	v_cvt_pk_bf16_f32 v59, v58, v59
	v_cvt_pk_bf16_f32 v58, v56, v57
	v_cvt_pk_bf16_f32 v57, v62, v63
	v_cvt_pk_bf16_f32 v56, v60, v61
	v_add_u32_e32 v151, 0x80000, v148
	global_store_dwordx4 v151, v[56:59], s[74:75]
	v_lshlrev_b32_e32 v180, 16, v216
	v_and_b32_e32 v181, 0xffff0000, v216
	v_lshlrev_b32_e32 v182, 16, v217
	v_and_b32_e32 v183, 0xffff0000, v217
	v_lshlrev_b32_e32 v184, 16, v218
	v_and_b32_e32 v185, 0xffff0000, v218
	v_lshlrev_b32_e32 v186, 16, v219
	v_and_b32_e32 v187, 0xffff0000, v219
	v_pk_fma_f32 v[52:53], v[52:53], v[204:205], v[180:181]
	v_pk_fma_f32 v[54:55], v[54:55], v[206:207], v[182:183]
	v_pk_fma_f32 v[48:49], v[48:49], v[208:209], v[184:185]
	v_pk_fma_f32 v[50:51], v[50:51], v[210:211], v[186:187]
	v_cvt_pk_bf16_f32 v51, v50, v51
	v_cvt_pk_bf16_f32 v50, v48, v49
	v_cvt_pk_bf16_f32 v49, v54, v55
	v_cvt_pk_bf16_f32 v48, v52, v53
	v_add_u32_e32 v151, 0x80000, v148
	global_store_dwordx4 v151, v[48:51], s[74:75] offset:256
	v_lshlrev_b32_e32 v180, 16, v220
	v_and_b32_e32 v181, 0xffff0000, v220
	v_lshlrev_b32_e32 v182, 16, v221
	v_and_b32_e32 v183, 0xffff0000, v221
	v_lshlrev_b32_e32 v184, 16, v222
	v_and_b32_e32 v185, 0xffff0000, v222
	v_lshlrev_b32_e32 v186, 16, v223
	v_and_b32_e32 v187, 0xffff0000, v223
	v_pk_fma_f32 v[44:45], v[44:45], v[196:197], v[180:181]
	v_pk_fma_f32 v[46:47], v[46:47], v[198:199], v[182:183]
	v_pk_fma_f32 v[40:41], v[40:41], v[200:201], v[184:185]
	v_pk_fma_f32 v[42:43], v[42:43], v[202:203], v[186:187]
	v_cvt_pk_bf16_f32 v43, v42, v43
	v_cvt_pk_bf16_f32 v42, v40, v41
	v_cvt_pk_bf16_f32 v41, v46, v47
	v_cvt_pk_bf16_f32 v40, v44, v45
	v_add_u32_e32 v151, 0x90000, v148
	global_store_dwordx4 v151, v[40:43], s[74:75]
	v_lshlrev_b32_e32 v180, 16, v224
	v_and_b32_e32 v181, 0xffff0000, v224
	v_lshlrev_b32_e32 v182, 16, v225
	v_and_b32_e32 v183, 0xffff0000, v225
	v_lshlrev_b32_e32 v184, 16, v226
	v_and_b32_e32 v185, 0xffff0000, v226
	v_lshlrev_b32_e32 v186, 16, v227
	v_and_b32_e32 v187, 0xffff0000, v227
	v_pk_fma_f32 v[36:37], v[36:37], v[204:205], v[180:181]
	v_pk_fma_f32 v[38:39], v[38:39], v[206:207], v[182:183]
	v_pk_fma_f32 v[32:33], v[32:33], v[208:209], v[184:185]
	v_pk_fma_f32 v[34:35], v[34:35], v[210:211], v[186:187]
	v_cvt_pk_bf16_f32 v35, v34, v35
	v_cvt_pk_bf16_f32 v34, v32, v33
	v_cvt_pk_bf16_f32 v33, v38, v39
	v_cvt_pk_bf16_f32 v32, v36, v37
	v_add_u32_e32 v151, 0x90000, v148
	global_store_dwordx4 v151, v[32:35], s[74:75] offset:256
	v_lshlrev_b32_e32 v180, 16, v164
	v_and_b32_e32 v181, 0xffff0000, v164
	v_lshlrev_b32_e32 v182, 16, v165
	v_and_b32_e32 v183, 0xffff0000, v165
	v_lshlrev_b32_e32 v184, 16, v166
	v_and_b32_e32 v185, 0xffff0000, v166
	v_lshlrev_b32_e32 v186, 16, v167
	v_and_b32_e32 v187, 0xffff0000, v167
	v_pk_fma_f32 v[28:29], v[28:29], v[196:197], v[180:181]
	v_pk_fma_f32 v[30:31], v[30:31], v[198:199], v[182:183]
	v_pk_fma_f32 v[24:25], v[24:25], v[200:201], v[184:185]
	v_pk_fma_f32 v[26:27], v[26:27], v[202:203], v[186:187]
	v_cvt_pk_bf16_f32 v27, v26, v27
	v_cvt_pk_bf16_f32 v26, v24, v25
	v_cvt_pk_bf16_f32 v25, v30, v31
	v_cvt_pk_bf16_f32 v24, v28, v29
	v_add_u32_e32 v151, 0xa0000, v148
	global_store_dwordx4 v151, v[24:27], s[74:75]
	v_lshlrev_b32_e32 v180, 16, v168
	v_and_b32_e32 v181, 0xffff0000, v168
	v_lshlrev_b32_e32 v182, 16, v169
	v_and_b32_e32 v183, 0xffff0000, v169
	v_lshlrev_b32_e32 v184, 16, v170
	v_and_b32_e32 v185, 0xffff0000, v170
	v_lshlrev_b32_e32 v186, 16, v171
	v_and_b32_e32 v187, 0xffff0000, v171
	v_pk_fma_f32 v[20:21], v[20:21], v[204:205], v[180:181]
	v_pk_fma_f32 v[22:23], v[22:23], v[206:207], v[182:183]
	v_pk_fma_f32 v[16:17], v[16:17], v[208:209], v[184:185]
	v_pk_fma_f32 v[18:19], v[18:19], v[210:211], v[186:187]
	v_cvt_pk_bf16_f32 v19, v18, v19
	v_cvt_pk_bf16_f32 v18, v16, v17
	v_cvt_pk_bf16_f32 v17, v22, v23
	v_cvt_pk_bf16_f32 v16, v20, v21
	v_add_u32_e32 v151, 0xa0000, v148
	global_store_dwordx4 v151, v[16:19], s[74:75] offset:256
	v_lshlrev_b32_e32 v180, 16, v172
	v_and_b32_e32 v181, 0xffff0000, v172
	v_lshlrev_b32_e32 v182, 16, v173
	v_and_b32_e32 v183, 0xffff0000, v173
	v_lshlrev_b32_e32 v184, 16, v174
	v_and_b32_e32 v185, 0xffff0000, v174
	v_lshlrev_b32_e32 v186, 16, v175
	v_and_b32_e32 v187, 0xffff0000, v175
	v_pk_fma_f32 v[12:13], v[12:13], v[196:197], v[180:181]
	v_pk_fma_f32 v[14:15], v[14:15], v[198:199], v[182:183]
	v_pk_fma_f32 v[8:9], v[8:9], v[200:201], v[184:185]
	v_pk_fma_f32 v[10:11], v[10:11], v[202:203], v[186:187]
	v_cvt_pk_bf16_f32 v11, v10, v11
	v_cvt_pk_bf16_f32 v10, v8, v9
	v_cvt_pk_bf16_f32 v9, v14, v15
	v_cvt_pk_bf16_f32 v8, v12, v13
	v_add_u32_e32 v151, 0xb0000, v148
	global_store_dwordx4 v151, v[8:11], s[74:75]
	v_lshlrev_b32_e32 v180, 16, v176
	v_and_b32_e32 v181, 0xffff0000, v176
	v_lshlrev_b32_e32 v182, 16, v177
	v_and_b32_e32 v183, 0xffff0000, v177
	v_lshlrev_b32_e32 v184, 16, v178
	v_and_b32_e32 v185, 0xffff0000, v178
	v_lshlrev_b32_e32 v186, 16, v179
	v_and_b32_e32 v187, 0xffff0000, v179
	v_pk_fma_f32 v[4:5], v[4:5], v[204:205], v[180:181]
	v_pk_fma_f32 v[6:7], v[6:7], v[206:207], v[182:183]
	v_pk_fma_f32 v[0:1], v[0:1], v[208:209], v[184:185]
	v_pk_fma_f32 v[2:3], v[2:3], v[210:211], v[186:187]
	v_cvt_pk_bf16_f32 v3, v2, v3
	v_cvt_pk_bf16_f32 v2, v0, v1
	v_cvt_pk_bf16_f32 v1, v6, v7
	v_cvt_pk_bf16_f32 v0, v4, v5
	v_add_u32_e32 v151, 0xb0000, v148
	global_store_dwordx4 v151, v[0:3], s[74:75] offset:256
.Lepi_nl_mlpout0:
	s_cmpk_gt_u32 s63, 0x7d
	s_barrier
	s_cbranch_scc0 .LBB0_1030
	s_cmp_lg_u32 s53, 0
	s_cbranch_scc1 .Lepi_g0done_mlpout0
	s_lshl_b32 s15, s46, 8
	s_add_i32 s15, s15, s53
	v_or_b32_e32 v154, s15, v147
	s_add_i32 s17, s15, 0xffffe000
	v_lshl_or_b32 v150, s33, 8, v158
	s_lshr_b32 s17, s17, 12
	v_lshlrev_b32_e32 v148, 12, v154
	s_add_i32 s17, s17, 1
	s_cmp_gt_i32 s15, s58
	s_cselect_b32 s17, s17, 0
	s_mul_i32 s17, s17, s56
	v_lshl_add_u32 v148, v150, 1, v148
	s_add_u32 s20, s8, s17
	s_addc_u32 s21, s9, 0
	v_lshlrev_b32_e32 v149, 2, v150
	s_nop 0
	global_load_dwordx4 v[196:199], v149, s[20:21]
	global_load_dwordx4 v[200:203], v149, s[20:21] offset:16
	global_load_dwordx4 v[204:207], v149, s[20:21] offset:512
	global_load_dwordx4 v[208:211], v149, s[20:21] offset:528
	global_load_dwordx4 v[212:215], v148, s[74:75]
	global_load_dwordx4 v[216:219], v148, s[74:75] offset:256
	v_add_u32_e32 v151, 0x10000, v148
	global_load_dwordx4 v[220:223], v151, s[74:75]
	global_load_dwordx4 v[224:227], v151, s[74:75] offset:256
	v_add_u32_e32 v151, 0x20000, v148
	global_load_dwordx4 v[164:167], v151, s[74:75]
	global_load_dwordx4 v[168:171], v151, s[74:75] offset:256
	v_add_u32_e32 v151, 0x30000, v148
	global_load_dwordx4 v[172:175], v151, s[74:75]
	global_load_dwordx4 v[176:179], v151, s[74:75] offset:256
	s_waitcnt vmcnt(0)
	v_lshlrev_b32_e32 v180, 16, v212
	v_and_b32_e32 v181, 0xffff0000, v212
	v_lshlrev_b32_e32 v182, 16, v213
	v_and_b32_e32 v183, 0xffff0000, v213
	v_lshlrev_b32_e32 v184, 16, v214
	v_and_b32_e32 v185, 0xffff0000, v214
	v_lshlrev_b32_e32 v186, 16, v215
	v_and_b32_e32 v187, 0xffff0000, v215
	v_pk_fma_f32 v[124:125], v[124:125], v[196:197], v[180:181]
	v_pk_fma_f32 v[126:127], v[126:127], v[198:199], v[182:183]
	v_pk_fma_f32 v[120:121], v[120:121], v[200:201], v[184:185]
	v_pk_fma_f32 v[122:123], v[122:123], v[202:203], v[186:187]
	v_cvt_pk_bf16_f32 v123, v122, v123
	v_cvt_pk_bf16_f32 v122, v120, v121
	v_cvt_pk_bf16_f32 v121, v126, v127
	v_cvt_pk_bf16_f32 v120, v124, v125
	global_store_dwordx4 v148, v[120:123], s[74:75]
	v_lshlrev_b32_e32 v180, 16, v216
	v_and_b32_e32 v181, 0xffff0000, v216
	v_lshlrev_b32_e32 v182, 16, v217
	v_and_b32_e32 v183, 0xffff0000, v217
	v_lshlrev_b32_e32 v184, 16, v218
	v_and_b32_e32 v185, 0xffff0000, v218
	v_lshlrev_b32_e32 v186, 16, v219
	v_and_b32_e32 v187, 0xffff0000, v219
	v_pk_fma_f32 v[116:117], v[116:117], v[204:205], v[180:181]
	v_pk_fma_f32 v[118:119], v[118:119], v[206:207], v[182:183]
	v_pk_fma_f32 v[112:113], v[112:113], v[208:209], v[184:185]
	v_pk_fma_f32 v[114:115], v[114:115], v[210:211], v[186:187]
	v_cvt_pk_bf16_f32 v115, v114, v115
	v_cvt_pk_bf16_f32 v114, v112, v113
	v_cvt_pk_bf16_f32 v113, v118, v119
	v_cvt_pk_bf16_f32 v112, v116, v117
	global_store_dwordx4 v148, v[112:115], s[74:75] offset:256
	v_lshlrev_b32_e32 v180, 16, v220
	v_and_b32_e32 v181, 0xffff0000, v220
	v_lshlrev_b32_e32 v182, 16, v221
	v_and_b32_e32 v183, 0xffff0000, v221
	v_lshlrev_b32_e32 v184, 16, v222
	v_and_b32_e32 v185, 0xffff0000, v222
	v_lshlrev_b32_e32 v186, 16, v223
	v_and_b32_e32 v187, 0xffff0000, v223
	v_pk_fma_f32 v[108:109], v[108:109], v[196:197], v[180:181]
	v_pk_fma_f32 v[110:111], v[110:111], v[198:199], v[182:183]
	v_pk_fma_f32 v[104:105], v[104:105], v[200:201], v[184:185]
	v_pk_fma_f32 v[106:107], v[106:107], v[202:203], v[186:187]
	v_cvt_pk_bf16_f32 v107, v106, v107
	v_cvt_pk_bf16_f32 v106, v104, v105
	v_cvt_pk_bf16_f32 v105, v110, v111
	v_cvt_pk_bf16_f32 v104, v108, v109
	v_add_u32_e32 v151, 0x10000, v148
	global_store_dwordx4 v151, v[104:107], s[74:75]
	v_lshlrev_b32_e32 v180, 16, v224
	v_and_b32_e32 v181, 0xffff0000, v224
	v_lshlrev_b32_e32 v182, 16, v225
	v_and_b32_e32 v183, 0xffff0000, v225
	v_lshlrev_b32_e32 v184, 16, v226
	v_and_b32_e32 v185, 0xffff0000, v226
	v_lshlrev_b32_e32 v186, 16, v227
	v_and_b32_e32 v187, 0xffff0000, v227
	v_pk_fma_f32 v[100:101], v[100:101], v[204:205], v[180:181]
	v_pk_fma_f32 v[102:103], v[102:103], v[206:207], v[182:183]
	v_pk_fma_f32 v[96:97], v[96:97], v[208:209], v[184:185]
	v_pk_fma_f32 v[98:99], v[98:99], v[210:211], v[186:187]
	v_cvt_pk_bf16_f32 v99, v98, v99
	v_cvt_pk_bf16_f32 v98, v96, v97
	v_cvt_pk_bf16_f32 v97, v102, v103
	v_cvt_pk_bf16_f32 v96, v100, v101
	v_add_u32_e32 v151, 0x10000, v148
	global_store_dwordx4 v151, v[96:99], s[74:75] offset:256
	v_add_u32_e32 v151, 0x80000, v148
	global_load_dwordx4 v[212:215], v151, s[74:75]
	global_load_dwordx4 v[216:219], v151, s[74:75] offset:256
	v_add_u32_e32 v151, 0x90000, v148
	global_load_dwordx4 v[220:223], v151, s[74:75]
	global_load_dwordx4 v[224:227], v151, s[74:75] offset:256
	v_lshlrev_b32_e32 v180, 16, v164
	v_and_b32_e32 v181, 0xffff0000, v164
	v_lshlrev_b32_e32 v182, 16, v165
	v_and_b32_e32 v183, 0xffff0000, v165
	v_lshlrev_b32_e32 v184, 16, v166
	v_and_b32_e32 v185, 0xffff0000, v166
	v_lshlrev_b32_e32 v186, 16, v167
	v_and_b32_e32 v187, 0xffff0000, v167
	v_pk_fma_f32 v[92:93], v[92:93], v[196:197], v[180:181]
	v_pk_fma_f32 v[94:95], v[94:95], v[198:199], v[182:183]
	v_pk_fma_f32 v[88:89], v[88:89], v[200:201], v[184:185]
	v_pk_fma_f32 v[90:91], v[90:91], v[202:203], v[186:187]
	v_cvt_pk_bf16_f32 v91, v90, v91
	v_cvt_pk_bf16_f32 v90, v88, v89
	v_cvt_pk_bf16_f32 v89, v94, v95
	v_cvt_pk_bf16_f32 v88, v92, v93
	v_add_u32_e32 v151, 0x20000, v148
	global_store_dwordx4 v151, v[88:91], s[74:75]
	v_lshlrev_b32_e32 v180, 16, v168
	v_and_b32_e32 v181, 0xffff0000, v168
	v_lshlrev_b32_e32 v182, 16, v169
	v_and_b32_e32 v183, 0xffff0000, v169
	v_lshlrev_b32_e32 v184, 16, v170
	v_and_b32_e32 v185, 0xffff0000, v170
	v_lshlrev_b32_e32 v186, 16, v171
	v_and_b32_e32 v187, 0xffff0000, v171
	v_pk_fma_f32 v[84:85], v[84:85], v[204:205], v[180:181]
	v_pk_fma_f32 v[86:87], v[86:87], v[206:207], v[182:183]
	v_pk_fma_f32 v[80:81], v[80:81], v[208:209], v[184:185]
	v_pk_fma_f32 v[82:83], v[82:83], v[210:211], v[186:187]
	v_cvt_pk_bf16_f32 v83, v82, v83
	v_cvt_pk_bf16_f32 v82, v80, v81
	v_cvt_pk_bf16_f32 v81, v86, v87
	v_cvt_pk_bf16_f32 v80, v84, v85
	v_add_u32_e32 v151, 0x20000, v148
	global_store_dwordx4 v151, v[80:83], s[74:75] offset:256
	v_lshlrev_b32_e32 v180, 16, v172
	v_and_b32_e32 v181, 0xffff0000, v172
	v_lshlrev_b32_e32 v182, 16, v173
	v_and_b32_e32 v183, 0xffff0000, v173
	v_lshlrev_b32_e32 v184, 16, v174
	v_and_b32_e32 v185, 0xffff0000, v174
	v_lshlrev_b32_e32 v186, 16, v175
	v_and_b32_e32 v187, 0xffff0000, v175
	v_pk_fma_f32 v[76:77], v[76:77], v[196:197], v[180:181]
	v_pk_fma_f32 v[78:79], v[78:79], v[198:199], v[182:183]
	v_pk_fma_f32 v[72:73], v[72:73], v[200:201], v[184:185]
	v_pk_fma_f32 v[74:75], v[74:75], v[202:203], v[186:187]
	v_cvt_pk_bf16_f32 v75, v74, v75
	v_cvt_pk_bf16_f32 v74, v72, v73
	v_cvt_pk_bf16_f32 v73, v78, v79
	v_cvt_pk_bf16_f32 v72, v76, v77
	v_add_u32_e32 v151, 0x30000, v148
	global_store_dwordx4 v151, v[72:75], s[74:75]
	v_lshlrev_b32_e32 v180, 16, v176
	v_and_b32_e32 v181, 0xffff0000, v176
	v_lshlrev_b32_e32 v182, 16, v177
	v_and_b32_e32 v183, 0xffff0000, v177
	v_lshlrev_b32_e32 v184, 16, v178
	v_and_b32_e32 v185, 0xffff0000, v178
	v_lshlrev_b32_e32 v186, 16, v179
	v_and_b32_e32 v187, 0xffff0000, v179
	v_pk_fma_f32 v[68:69], v[68:69], v[204:205], v[180:181]
	v_pk_fma_f32 v[70:71], v[70:71], v[206:207], v[182:183]
	v_pk_fma_f32 v[64:65], v[64:65], v[208:209], v[184:185]
	v_pk_fma_f32 v[66:67], v[66:67], v[210:211], v[186:187]
	v_cvt_pk_bf16_f32 v67, v66, v67
	v_cvt_pk_bf16_f32 v66, v64, v65
	v_cvt_pk_bf16_f32 v65, v70, v71
	v_cvt_pk_bf16_f32 v64, v68, v69
	v_add_u32_e32 v151, 0x30000, v148
	global_store_dwordx4 v151, v[64:67], s[74:75] offset:256
	v_add_u32_e32 v151, 0xa0000, v148
	global_load_dwordx4 v[164:167], v151, s[74:75]
	global_load_dwordx4 v[168:171], v151, s[74:75] offset:256
	v_add_u32_e32 v151, 0xb0000, v148
	global_load_dwordx4 v[172:175], v151, s[74:75]
	global_load_dwordx4 v[176:179], v151, s[74:75] offset:256
	s_waitcnt vmcnt(0)
	v_lshlrev_b32_e32 v180, 16, v212
	v_and_b32_e32 v181, 0xffff0000, v212
	v_lshlrev_b32_e32 v182, 16, v213
	v_and_b32_e32 v183, 0xffff0000, v213
	v_lshlrev_b32_e32 v184, 16, v214
	v_and_b32_e32 v185, 0xffff0000, v214
	v_lshlrev_b32_e32 v186, 16, v215
	v_and_b32_e32 v187, 0xffff0000, v215
	v_pk_fma_f32 v[60:61], v[60:61], v[196:197], v[180:181]
	v_pk_fma_f32 v[62:63], v[62:63], v[198:199], v[182:183]
	v_pk_fma_f32 v[56:57], v[56:57], v[200:201], v[184:185]
	v_pk_fma_f32 v[58:59], v[58:59], v[202:203], v[186:187]
	v_cvt_pk_bf16_f32 v59, v58, v59
	v_cvt_pk_bf16_f32 v58, v56, v57
	v_cvt_pk_bf16_f32 v57, v62, v63
	v_cvt_pk_bf16_f32 v56, v60, v61
	v_add_u32_e32 v151, 0x80000, v148
	global_store_dwordx4 v151, v[56:59], s[74:75]
	v_lshlrev_b32_e32 v180, 16, v216
	v_and_b32_e32 v181, 0xffff0000, v216
	v_lshlrev_b32_e32 v182, 16, v217
	v_and_b32_e32 v183, 0xffff0000, v217
	v_lshlrev_b32_e32 v184, 16, v218
	v_and_b32_e32 v185, 0xffff0000, v218
	v_lshlrev_b32_e32 v186, 16, v219
	v_and_b32_e32 v187, 0xffff0000, v219
	v_pk_fma_f32 v[52:53], v[52:53], v[204:205], v[180:181]
	v_pk_fma_f32 v[54:55], v[54:55], v[206:207], v[182:183]
	v_pk_fma_f32 v[48:49], v[48:49], v[208:209], v[184:185]
	v_pk_fma_f32 v[50:51], v[50:51], v[210:211], v[186:187]
	v_cvt_pk_bf16_f32 v51, v50, v51
	v_cvt_pk_bf16_f32 v50, v48, v49
	v_cvt_pk_bf16_f32 v49, v54, v55
	v_cvt_pk_bf16_f32 v48, v52, v53
	v_add_u32_e32 v151, 0x80000, v148
	global_store_dwordx4 v151, v[48:51], s[74:75] offset:256
	v_lshlrev_b32_e32 v180, 16, v220
	v_and_b32_e32 v181, 0xffff0000, v220
	v_lshlrev_b32_e32 v182, 16, v221
	v_and_b32_e32 v183, 0xffff0000, v221
	v_lshlrev_b32_e32 v184, 16, v222
	v_and_b32_e32 v185, 0xffff0000, v222
	v_lshlrev_b32_e32 v186, 16, v223
	v_and_b32_e32 v187, 0xffff0000, v223
	v_pk_fma_f32 v[44:45], v[44:45], v[196:197], v[180:181]
	v_pk_fma_f32 v[46:47], v[46:47], v[198:199], v[182:183]
	v_pk_fma_f32 v[40:41], v[40:41], v[200:201], v[184:185]
	v_pk_fma_f32 v[42:43], v[42:43], v[202:203], v[186:187]
	v_cvt_pk_bf16_f32 v43, v42, v43
	v_cvt_pk_bf16_f32 v42, v40, v41
	v_cvt_pk_bf16_f32 v41, v46, v47
	v_cvt_pk_bf16_f32 v40, v44, v45
	v_add_u32_e32 v151, 0x90000, v148
	global_store_dwordx4 v151, v[40:43], s[74:75]
	v_lshlrev_b32_e32 v180, 16, v224
	v_and_b32_e32 v181, 0xffff0000, v224
	v_lshlrev_b32_e32 v182, 16, v225
	v_and_b32_e32 v183, 0xffff0000, v225
	v_lshlrev_b32_e32 v184, 16, v226
	v_and_b32_e32 v185, 0xffff0000, v226
	v_lshlrev_b32_e32 v186, 16, v227
	v_and_b32_e32 v187, 0xffff0000, v227
	v_pk_fma_f32 v[36:37], v[36:37], v[204:205], v[180:181]
	v_pk_fma_f32 v[38:39], v[38:39], v[206:207], v[182:183]
	v_pk_fma_f32 v[32:33], v[32:33], v[208:209], v[184:185]
	v_pk_fma_f32 v[34:35], v[34:35], v[210:211], v[186:187]
	v_cvt_pk_bf16_f32 v35, v34, v35
	v_cvt_pk_bf16_f32 v34, v32, v33
	v_cvt_pk_bf16_f32 v33, v38, v39
	v_cvt_pk_bf16_f32 v32, v36, v37
	v_add_u32_e32 v151, 0x90000, v148
	global_store_dwordx4 v151, v[32:35], s[74:75] offset:256
	v_lshlrev_b32_e32 v180, 16, v164
	v_and_b32_e32 v181, 0xffff0000, v164
	v_lshlrev_b32_e32 v182, 16, v165
	v_and_b32_e32 v183, 0xffff0000, v165
	v_lshlrev_b32_e32 v184, 16, v166
	v_and_b32_e32 v185, 0xffff0000, v166
	v_lshlrev_b32_e32 v186, 16, v167
	v_and_b32_e32 v187, 0xffff0000, v167
	v_pk_fma_f32 v[28:29], v[28:29], v[196:197], v[180:181]
	v_pk_fma_f32 v[30:31], v[30:31], v[198:199], v[182:183]
	v_pk_fma_f32 v[24:25], v[24:25], v[200:201], v[184:185]
	v_pk_fma_f32 v[26:27], v[26:27], v[202:203], v[186:187]
	v_cvt_pk_bf16_f32 v27, v26, v27
	v_cvt_pk_bf16_f32 v26, v24, v25
	v_cvt_pk_bf16_f32 v25, v30, v31
	v_cvt_pk_bf16_f32 v24, v28, v29
	v_add_u32_e32 v151, 0xa0000, v148
	global_store_dwordx4 v151, v[24:27], s[74:75]
	v_lshlrev_b32_e32 v180, 16, v168
	v_and_b32_e32 v181, 0xffff0000, v168
	v_lshlrev_b32_e32 v182, 16, v169
	v_and_b32_e32 v183, 0xffff0000, v169
	v_lshlrev_b32_e32 v184, 16, v170
	v_and_b32_e32 v185, 0xffff0000, v170
	v_lshlrev_b32_e32 v186, 16, v171
	v_and_b32_e32 v187, 0xffff0000, v171
	v_pk_fma_f32 v[20:21], v[20:21], v[204:205], v[180:181]
	v_pk_fma_f32 v[22:23], v[22:23], v[206:207], v[182:183]
	v_pk_fma_f32 v[16:17], v[16:17], v[208:209], v[184:185]
	v_pk_fma_f32 v[18:19], v[18:19], v[210:211], v[186:187]
	v_cvt_pk_bf16_f32 v19, v18, v19
	v_cvt_pk_bf16_f32 v18, v16, v17
	v_cvt_pk_bf16_f32 v17, v22, v23
	v_cvt_pk_bf16_f32 v16, v20, v21
	v_add_u32_e32 v151, 0xa0000, v148
	global_store_dwordx4 v151, v[16:19], s[74:75] offset:256
	v_lshlrev_b32_e32 v180, 16, v172
	v_and_b32_e32 v181, 0xffff0000, v172
	v_lshlrev_b32_e32 v182, 16, v173
	v_and_b32_e32 v183, 0xffff0000, v173
	v_lshlrev_b32_e32 v184, 16, v174
	v_and_b32_e32 v185, 0xffff0000, v174
	v_lshlrev_b32_e32 v186, 16, v175
	v_and_b32_e32 v187, 0xffff0000, v175
	v_pk_fma_f32 v[12:13], v[12:13], v[196:197], v[180:181]
	v_pk_fma_f32 v[14:15], v[14:15], v[198:199], v[182:183]
	v_pk_fma_f32 v[8:9], v[8:9], v[200:201], v[184:185]
	v_pk_fma_f32 v[10:11], v[10:11], v[202:203], v[186:187]
	v_cvt_pk_bf16_f32 v11, v10, v11
	v_cvt_pk_bf16_f32 v10, v8, v9
	v_cvt_pk_bf16_f32 v9, v14, v15
	v_cvt_pk_bf16_f32 v8, v12, v13
	v_add_u32_e32 v151, 0xb0000, v148
	global_store_dwordx4 v151, v[8:11], s[74:75]
	v_lshlrev_b32_e32 v180, 16, v176
	v_and_b32_e32 v181, 0xffff0000, v176
	v_lshlrev_b32_e32 v182, 16, v177
	v_and_b32_e32 v183, 0xffff0000, v177
	v_lshlrev_b32_e32 v184, 16, v178
	v_and_b32_e32 v185, 0xffff0000, v178
	v_lshlrev_b32_e32 v186, 16, v179
	v_and_b32_e32 v187, 0xffff0000, v179
	v_pk_fma_f32 v[4:5], v[4:5], v[204:205], v[180:181]
	v_pk_fma_f32 v[6:7], v[6:7], v[206:207], v[182:183]
	v_pk_fma_f32 v[0:1], v[0:1], v[208:209], v[184:185]
	v_pk_fma_f32 v[2:3], v[2:3], v[210:211], v[186:187]
	v_cvt_pk_bf16_f32 v3, v2, v3
	v_cvt_pk_bf16_f32 v2, v0, v1
	v_cvt_pk_bf16_f32 v1, v6, v7
	v_cvt_pk_bf16_f32 v0, v4, v5
	v_add_u32_e32 v151, 0xb0000, v148
	global_store_dwordx4 v151, v[0:3], s[74:75] offset:256
.Lepi_g0done_mlpout0:
	s_mov_b32 s33, s14
	s_mov_b32 s46, s16
	s_mov_b64 s[50:51], s[44:45]
	s_mov_b64 s[48:49], s[18:19]
	s_and_b64 vcc, exec, s[0:1]
	s_cbranch_vccz .LBB0_1027
	s_waitcnt vmcnt(0)
	s_cmpk_gt_u32 s12, 0xff
	s_cbranch_scc1 .LBB0_1034
	s_barrier

.LBB0_1346:
	ds_read_b128 v[148:151], v158
	ds_read_b128 v[152:155], v158 offset:1024
	ds_read_b128 v[162:165], v158 offset:2048
	ds_read_b128 v[166:169], v158 offset:3072
	s_add_u32 s20, s38, 0xfff80080
	s_addc_u32 s21, s39, -1
	s_cmp_eq_u32 s61, 28
	s_cselect_b32 s21, s17, s21
	s_cselect_b32 s20, s57, s20
	s_cselect_b32 s45, s15, s60
	s_cselect_b32 s44, s58, s59
	v_lshl_add_u64 v[190:191], s[38:39], 0, v[136:137]
	s_add_i32 m0, s37, 0xc000
	ds_read_b128 v[170:173], v159
	ds_read_b128 v[174:177], v159 offset:1024
	ds_read_b128 v[178:181], v159 offset:2048
	ds_read_b128 v[182:185], v159 offset:3072
	ds_read_b128 v[186:189], v159 offset:4096
	ds_read_b128 v[196:199], v159 offset:5120
	ds_read_b128 v[200:203], v159 offset:6144
	ds_read_b128 v[204:207], v159 offset:7168
	global_load_lds_dwordx4 v[190:191], off
	v_lshl_add_u64 v[190:191], s[38:39], 0, v[138:139]
	s_add_i32 m0, s37, 0xe000
	s_nop 0
	global_load_lds_dwordx4 v[190:191], off
	s_waitcnt lgkmcnt(8)
	s_barrier
	s_waitcnt lgkmcnt(0)
	s_setprio 1
	s_waitcnt lgkmcnt(0)
	v_mfma_f32_16x16x32_bf16 v[124:127], v[148:151], v[170:173], v[124:127]
	v_mfma_f32_16x16x32_bf16 v[120:123], v[162:165], v[170:173], v[120:123]
	v_mfma_f32_16x16x32_bf16 v[108:111], v[148:151], v[178:181], v[108:111]
	v_mfma_f32_16x16x32_bf16 v[104:107], v[162:165], v[178:181], v[104:107]
	v_mfma_f32_16x16x32_bf16 v[92:95], v[148:151], v[186:189], v[92:95]
	v_mfma_f32_16x16x32_bf16 v[88:91], v[162:165], v[186:189], v[88:91]
	v_mfma_f32_16x16x32_bf16 v[76:79], v[148:151], v[200:203], v[76:79]
	v_mfma_f32_16x16x32_bf16 v[72:75], v[162:165], v[200:203], v[72:75]
	v_mfma_f32_16x16x32_bf16 v[124:127], v[152:155], v[174:177], v[124:127]
	v_mfma_f32_16x16x32_bf16 v[120:123], v[166:169], v[174:177], v[120:123]
	v_mfma_f32_16x16x32_bf16 v[108:111], v[152:155], v[182:185], v[108:111]
	v_mfma_f32_16x16x32_bf16 v[104:107], v[166:169], v[182:185], v[104:107]
	v_mfma_f32_16x16x32_bf16 v[92:95], v[152:155], v[196:199], v[92:95]
	v_mfma_f32_16x16x32_bf16 v[88:91], v[166:169], v[196:199], v[88:91]
	v_mfma_f32_16x16x32_bf16 v[76:79], v[152:155], v[204:207], v[76:79]
	v_mfma_f32_16x16x32_bf16 v[72:75], v[166:169], v[204:207], v[72:75]
	s_setprio 0
	s_barrier
	s_add_i32 s62, s53, s23
	v_lshl_add_u64 v[190:191], s[44:45], 0, v[132:133]
	s_mov_b32 m0, s62
	ds_read_b128 v[208:211], v160
	ds_read_b128 v[212:215], v160 offset:1024
	ds_read_b128 v[216:219], v160 offset:2048
	ds_read_b128 v[220:223], v160 offset:3072
	global_load_lds_dwordx4 v[190:191], off
	v_lshl_add_u64 v[224:225], s[44:45], 0, v[128:129]
	s_add_i32 m0, s62, 0x2000
	s_nop 0
	global_load_lds_dwordx4 v[224:225], off
	s_barrier
	s_waitcnt lgkmcnt(0)
	s_setprio 1
	s_waitcnt lgkmcnt(0)
	v_mfma_f32_16x16x32_bf16 v[116:119], v[208:211], v[170:173], v[116:119]
	v_mfma_f32_16x16x32_bf16 v[112:115], v[216:219], v[170:173], v[112:115]
	v_mfma_f32_16x16x32_bf16 v[100:103], v[208:211], v[178:181], v[100:103]
	v_mfma_f32_16x16x32_bf16 v[96:99], v[216:219], v[178:181], v[96:99]
	v_mfma_f32_16x16x32_bf16 v[84:87], v[208:211], v[186:189], v[84:87]
	v_mfma_f32_16x16x32_bf16 v[80:83], v[216:219], v[186:189], v[80:83]
	v_mfma_f32_16x16x32_bf16 v[68:71], v[208:211], v[200:203], v[68:71]
	v_mfma_f32_16x16x32_bf16 v[64:67], v[216:219], v[200:203], v[64:67]
	v_mfma_f32_16x16x32_bf16 v[116:119], v[212:215], v[174:177], v[116:119]
	v_mfma_f32_16x16x32_bf16 v[112:115], v[220:223], v[174:177], v[112:115]
	v_mfma_f32_16x16x32_bf16 v[100:103], v[212:215], v[182:185], v[100:103]
	v_mfma_f32_16x16x32_bf16 v[96:99], v[220:223], v[182:185], v[96:99]
	v_mfma_f32_16x16x32_bf16 v[84:87], v[212:215], v[196:199], v[84:87]
	v_mfma_f32_16x16x32_bf16 v[80:83], v[220:223], v[196:199], v[80:83]
	v_mfma_f32_16x16x32_bf16 v[68:71], v[212:215], v[204:207], v[68:71]
	v_mfma_f32_16x16x32_bf16 v[64:67], v[220:223], v[204:207], v[64:67]
	s_setprio 0
	s_mov_b32 m0, s37
	v_lshl_add_u64 v[226:227], s[20:21], 0, v[134:135]
	s_barrier
	ds_read_b128 v[170:173], v159 offset:16384
	ds_read_b128 v[174:177], v159 offset:17408
	ds_read_b128 v[178:181], v159 offset:18432
	ds_read_b128 v[182:185], v159 offset:19456
	ds_read_b128 v[186:189], v159 offset:20480
	ds_read_b128 v[196:199], v159 offset:21504
	ds_read_b128 v[200:203], v159 offset:22528
	ds_read_b128 v[204:207], v159 offset:23552
	global_load_lds_dwordx4 v[226:227], off
	v_lshl_add_u64 v[228:229], s[20:21], 0, v[130:131]
	s_mov_b32 m0, s47
	s_nop 0
	global_load_lds_dwordx4 v[228:229], off
	s_barrier
	s_waitcnt lgkmcnt(0)
	s_setprio 1
	s_waitcnt lgkmcnt(0)
	v_mfma_f32_16x16x32_bf16 v[60:63], v[148:151], v[170:173], v[60:63]
	v_mfma_f32_16x16x32_bf16 v[56:59], v[162:165], v[170:173], v[56:59]
	v_mfma_f32_16x16x32_bf16 v[44:47], v[148:151], v[178:181], v[44:47]
	v_mfma_f32_16x16x32_bf16 v[40:43], v[162:165], v[178:181], v[40:43]
	v_mfma_f32_16x16x32_bf16 v[28:31], v[148:151], v[186:189], v[28:31]
	v_mfma_f32_16x16x32_bf16 v[24:27], v[162:165], v[186:189], v[24:27]
	v_mfma_f32_16x16x32_bf16 v[12:15], v[148:151], v[200:203], v[12:15]
	v_mfma_f32_16x16x32_bf16 v[8:11], v[162:165], v[200:203], v[8:11]
	v_mfma_f32_16x16x32_bf16 v[60:63], v[152:155], v[174:177], v[60:63]
	v_mfma_f32_16x16x32_bf16 v[56:59], v[166:169], v[174:177], v[56:59]
	v_mfma_f32_16x16x32_bf16 v[44:47], v[152:155], v[182:185], v[44:47]
	v_mfma_f32_16x16x32_bf16 v[40:43], v[166:169], v[182:185], v[40:43]
	v_mfma_f32_16x16x32_bf16 v[28:31], v[152:155], v[196:199], v[28:31]
	v_mfma_f32_16x16x32_bf16 v[24:27], v[166:169], v[196:199], v[24:27]
	v_mfma_f32_16x16x32_bf16 v[12:15], v[152:155], v[204:207], v[12:15]
	v_mfma_f32_16x16x32_bf16 v[8:11], v[166:169], v[204:207], v[8:11]
	s_setprio 0
	s_barrier
	s_add_u32 s62, s44, 0x80000
	s_addc_u32 s63, s45, 0
	s_add_i32 s64, s55, s23
	v_lshl_add_u64 v[148:149], s[62:63], 0, v[132:133]
	s_mov_b32 m0, s64
	s_nop 0
	global_load_lds_dwordx4 v[148:149], off
	v_lshl_add_u64 v[148:149], s[62:63], 0, v[128:129]
	s_add_i32 m0, s64, 0x2000
	s_nop 0
	global_load_lds_dwordx4 v[148:149], off
	s_waitcnt vmcnt(6)
	s_barrier
	s_setprio 1
	v_mfma_f32_16x16x32_bf16 v[52:55], v[208:211], v[170:173], v[52:55]
	v_mfma_f32_16x16x32_bf16 v[48:51], v[216:219], v[170:173], v[48:51]
	v_mfma_f32_16x16x32_bf16 v[36:39], v[208:211], v[178:181], v[36:39]
	v_mfma_f32_16x16x32_bf16 v[32:35], v[216:219], v[178:181], v[32:35]
	v_mfma_f32_16x16x32_bf16 v[20:23], v[208:211], v[186:189], v[20:23]
	v_mfma_f32_16x16x32_bf16 v[16:19], v[216:219], v[186:189], v[16:19]
	v_mfma_f32_16x16x32_bf16 v[4:7], v[208:211], v[200:203], v[4:7]
	v_mfma_f32_16x16x32_bf16 v[0:3], v[216:219], v[200:203], v[0:3]
	v_mfma_f32_16x16x32_bf16 v[52:55], v[212:215], v[174:177], v[52:55]
	v_mfma_f32_16x16x32_bf16 v[48:51], v[220:223], v[174:177], v[48:51]
	v_mfma_f32_16x16x32_bf16 v[36:39], v[212:215], v[182:185], v[36:39]
	v_mfma_f32_16x16x32_bf16 v[32:35], v[220:223], v[182:185], v[32:35]
	v_mfma_f32_16x16x32_bf16 v[20:23], v[212:215], v[196:199], v[20:23]
	v_mfma_f32_16x16x32_bf16 v[16:19], v[220:223], v[196:199], v[16:19]
	v_mfma_f32_16x16x32_bf16 v[4:7], v[212:215], v[204:207], v[4:7]
	v_mfma_f32_16x16x32_bf16 v[0:3], v[220:223], v[204:207], v[0:3]
	s_setprio 0
	s_add_i32 s62, 0, 0x18000
	v_add_u32_e32 v161, s62, v147
	s_barrier
	ds_read_b128 v[148:151], v161
	ds_read_b128 v[152:155], v161 offset:1024
	ds_read_b128 v[162:165], v161 offset:2048
	ds_read_b128 v[166:169], v161 offset:3072
	s_add_u32 s20, s20, 0x80000
	s_addc_u32 s21, s21, 0
	s_mov_b32 m0, s48
	v_lshl_add_u64 v[208:209], s[20:21], 0, v[134:135]
	ds_read_b128 v[170:173], v159 offset:32768
	ds_read_b128 v[174:177], v159 offset:33792
	ds_read_b128 v[178:181], v159 offset:34816
	ds_read_b128 v[182:185], v159 offset:35840
	ds_read_b128 v[186:189], v159 offset:36864
	ds_read_b128 v[196:199], v159 offset:37888
	ds_read_b128 v[200:203], v159 offset:38912
	ds_read_b128 v[204:207], v159 offset:39936
	global_load_lds_dwordx4 v[208:209], off
	v_lshl_add_u64 v[208:209], s[20:21], 0, v[130:131]
	s_mov_b32 m0, s49
	s_nop 0
	global_load_lds_dwordx4 v[208:209], off
	s_waitcnt lgkmcnt(8)
	s_barrier
	s_waitcnt lgkmcnt(0)
	s_setprio 1
	s_waitcnt lgkmcnt(0)
	v_mfma_f32_16x16x32_bf16 v[124:127], v[148:151], v[170:173], v[124:127]
	v_mfma_f32_16x16x32_bf16 v[120:123], v[162:165], v[170:173], v[120:123]
	v_mfma_f32_16x16x32_bf16 v[108:111], v[148:151], v[178:181], v[108:111]
	v_mfma_f32_16x16x32_bf16 v[104:107], v[162:165], v[178:181], v[104:107]
	v_mfma_f32_16x16x32_bf16 v[92:95], v[148:151], v[186:189], v[92:95]
	v_mfma_f32_16x16x32_bf16 v[88:91], v[162:165], v[186:189], v[88:91]
	v_mfma_f32_16x16x32_bf16 v[76:79], v[148:151], v[200:203], v[76:79]
	v_mfma_f32_16x16x32_bf16 v[72:75], v[162:165], v[200:203], v[72:75]
	v_mfma_f32_16x16x32_bf16 v[124:127], v[152:155], v[174:177], v[124:127]
	v_mfma_f32_16x16x32_bf16 v[120:123], v[166:169], v[174:177], v[120:123]
	v_mfma_f32_16x16x32_bf16 v[108:111], v[152:155], v[182:185], v[108:111]
	v_mfma_f32_16x16x32_bf16 v[104:107], v[166:169], v[182:185], v[104:107]
	v_mfma_f32_16x16x32_bf16 v[92:95], v[152:155], v[196:199], v[92:95]
	v_mfma_f32_16x16x32_bf16 v[88:91], v[166:169], v[196:199], v[88:91]
	v_mfma_f32_16x16x32_bf16 v[76:79], v[152:155], v[204:207], v[76:79]
	v_mfma_f32_16x16x32_bf16 v[72:75], v[166:169], v[204:207], v[72:75]
	s_setprio 0
	s_barrier
	s_add_i32 s63, 0, 0x1c000
	s_add_i32 s20, s62, s23
	v_add_u32_e32 v161, s63, v147
	v_lshl_add_u64 v[190:191], v[190:191], 0, s[10:11]
	s_mov_b32 m0, s20
	ds_read_b128 v[208:211], v161
	ds_read_b128 v[212:215], v161 offset:1024
	ds_read_b128 v[216:219], v161 offset:2048
	ds_read_b128 v[220:223], v161 offset:3072
	global_load_lds_dwordx4 v[190:191], off
	v_lshl_add_u64 v[190:191], v[224:225], 0, s[10:11]
	s_add_i32 m0, s20, 0x2000
	s_nop 0
	global_load_lds_dwordx4 v[190:191], off
	s_barrier
	s_waitcnt lgkmcnt(0)
	s_setprio 1
	s_waitcnt lgkmcnt(0)
	v_mfma_f32_16x16x32_bf16 v[116:119], v[208:211], v[170:173], v[116:119]
	v_mfma_f32_16x16x32_bf16 v[112:115], v[216:219], v[170:173], v[112:115]
	v_mfma_f32_16x16x32_bf16 v[100:103], v[208:211], v[178:181], v[100:103]
	v_mfma_f32_16x16x32_bf16 v[96:99], v[216:219], v[178:181], v[96:99]
	v_mfma_f32_16x16x32_bf16 v[84:87], v[208:211], v[186:189], v[84:87]
	v_mfma_f32_16x16x32_bf16 v[80:83], v[216:219], v[186:189], v[80:83]
	v_mfma_f32_16x16x32_bf16 v[68:71], v[208:211], v[200:203], v[68:71]
	v_mfma_f32_16x16x32_bf16 v[64:67], v[216:219], v[200:203], v[64:67]
	v_mfma_f32_16x16x32_bf16 v[116:119], v[212:215], v[174:177], v[116:119]
	v_mfma_f32_16x16x32_bf16 v[112:115], v[220:223], v[174:177], v[112:115]
	v_mfma_f32_16x16x32_bf16 v[100:103], v[212:215], v[182:185], v[100:103]
	v_mfma_f32_16x16x32_bf16 v[96:99], v[220:223], v[182:185], v[96:99]
	v_mfma_f32_16x16x32_bf16 v[84:87], v[212:215], v[196:199], v[84:87]
	v_mfma_f32_16x16x32_bf16 v[80:83], v[220:223], v[196:199], v[80:83]
	v_mfma_f32_16x16x32_bf16 v[68:71], v[212:215], v[204:207], v[68:71]
	v_mfma_f32_16x16x32_bf16 v[64:67], v[220:223], v[204:207], v[64:67]
	s_setprio 0
	s_mov_b32 m0, s34
	v_lshl_add_u64 v[190:191], v[226:227], 0, s[10:11]
	s_barrier
	ds_read_b128 v[170:173], v159 offset:49152
	ds_read_b128 v[174:177], v159 offset:50176
	ds_read_b128 v[178:181], v159 offset:51200
	ds_read_b128 v[182:185], v159 offset:52224
	ds_read_b128 v[186:189], v159 offset:53248
	ds_read_b128 v[196:199], v159 offset:54272
	ds_read_b128 v[200:203], v159 offset:55296
	ds_read_b128 v[204:207], v159 offset:56320
	global_load_lds_dwordx4 v[190:191], off
	v_lshl_add_u64 v[190:191], v[228:229], 0, s[10:11]
	s_mov_b32 m0, s35
	s_nop 0
	global_load_lds_dwordx4 v[190:191], off
	s_barrier
	s_waitcnt lgkmcnt(0)
	s_setprio 1
	s_waitcnt lgkmcnt(0)
	v_mfma_f32_16x16x32_bf16 v[60:63], v[148:151], v[170:173], v[60:63]
	v_mfma_f32_16x16x32_bf16 v[56:59], v[162:165], v[170:173], v[56:59]
	v_mfma_f32_16x16x32_bf16 v[44:47], v[148:151], v[178:181], v[44:47]
	v_mfma_f32_16x16x32_bf16 v[40:43], v[162:165], v[178:181], v[40:43]
	v_mfma_f32_16x16x32_bf16 v[28:31], v[148:151], v[186:189], v[28:31]
	v_mfma_f32_16x16x32_bf16 v[24:27], v[162:165], v[186:189], v[24:27]
	v_mfma_f32_16x16x32_bf16 v[12:15], v[148:151], v[200:203], v[12:15]
	v_mfma_f32_16x16x32_bf16 v[8:11], v[162:165], v[200:203], v[8:11]
	v_mfma_f32_16x16x32_bf16 v[60:63], v[152:155], v[174:177], v[60:63]
	v_mfma_f32_16x16x32_bf16 v[56:59], v[166:169], v[174:177], v[56:59]
	v_mfma_f32_16x16x32_bf16 v[44:47], v[152:155], v[182:185], v[44:47]
	v_mfma_f32_16x16x32_bf16 v[40:43], v[166:169], v[182:185], v[40:43]
	v_mfma_f32_16x16x32_bf16 v[28:31], v[152:155], v[196:199], v[28:31]
	v_mfma_f32_16x16x32_bf16 v[24:27], v[166:169], v[196:199], v[24:27]
	v_mfma_f32_16x16x32_bf16 v[12:15], v[152:155], v[204:207], v[12:15]
	v_mfma_f32_16x16x32_bf16 v[8:11], v[166:169], v[204:207], v[8:11]
	s_setprio 0
	s_barrier
	s_add_u32 s20, s44, 0x80080
	s_addc_u32 s21, s45, 0
	s_add_i32 s44, s63, s23
	v_lshl_add_u64 v[148:149], s[20:21], 0, v[132:133]
	s_mov_b32 m0, s44
	s_nop 0
	global_load_lds_dwordx4 v[148:149], off
	v_lshl_add_u64 v[148:149], s[20:21], 0, v[128:129]
	s_add_i32 m0, s44, 0x2000
	s_nop 0
	global_load_lds_dwordx4 v[148:149], off
	s_waitcnt vmcnt(6)
	s_barrier
	s_setprio 1
	v_mfma_f32_16x16x32_bf16 v[52:55], v[208:211], v[170:173], v[52:55]
	v_mfma_f32_16x16x32_bf16 v[48:51], v[216:219], v[170:173], v[48:51]
	v_mfma_f32_16x16x32_bf16 v[36:39], v[208:211], v[178:181], v[36:39]
	v_mfma_f32_16x16x32_bf16 v[32:35], v[216:219], v[178:181], v[32:35]
	v_mfma_f32_16x16x32_bf16 v[20:23], v[208:211], v[186:189], v[20:23]
	v_mfma_f32_16x16x32_bf16 v[16:19], v[216:219], v[186:189], v[16:19]
	v_mfma_f32_16x16x32_bf16 v[4:7], v[208:211], v[200:203], v[4:7]
	v_mfma_f32_16x16x32_bf16 v[0:3], v[216:219], v[200:203], v[0:3]
	v_mfma_f32_16x16x32_bf16 v[52:55], v[212:215], v[174:177], v[52:55]
	v_mfma_f32_16x16x32_bf16 v[48:51], v[220:223], v[174:177], v[48:51]
	v_mfma_f32_16x16x32_bf16 v[36:39], v[212:215], v[182:185], v[36:39]
	v_mfma_f32_16x16x32_bf16 v[32:35], v[220:223], v[182:185], v[32:35]
	v_mfma_f32_16x16x32_bf16 v[20:23], v[212:215], v[196:199], v[20:23]
	v_mfma_f32_16x16x32_bf16 v[16:19], v[220:223], v[196:199], v[16:19]
	v_mfma_f32_16x16x32_bf16 v[4:7], v[212:215], v[204:207], v[4:7]
	v_mfma_f32_16x16x32_bf16 v[0:3], v[220:223], v[204:207], v[0:3]
	s_setprio 0
	s_add_i32 s61, s61, 2
	s_add_u32 s38, s38, 0x100
	s_addc_u32 s39, s39, 0
	s_add_u32 s59, s59, 0x100
	s_addc_u32 s60, s60, 0
	s_cmp_gt_u32 s61, 29
	s_cbranch_scc0 .Lepi_nl_c_out
	s_cmp_lg_u32 s51, 64
	s_cbranch_scc1 .Lepi_nl_c_out
	s_lshl_b32 s15, s36, 8
	s_add_i32 s15, s15, s51
	v_or_b32_e32 v154, s15, v145
	s_add_i32 s17, s15, 0xffffe000
	v_lshl_or_b32 v150, s33, 8, v157
	s_lshr_b32 s17, s17, 12
	v_lshlrev_b32_e32 v148, 12, v154
	s_add_i32 s17, s17, 1
	s_cmp_gt_i32 s15, s56
	s_cselect_b32 s17, s17, 0
	s_mul_i32 s17, s17, s54
	v_lshl_add_u32 v148, v150, 1, v148
	s_add_u32 s20, s8, s17
	s_addc_u32 s21, s9, 0
	v_lshlrev_b32_e32 v149, 2, v150
	s_nop 0
	global_load_dwordx4 v[196:199], v149, s[20:21]
	global_load_dwordx4 v[200:203], v149, s[20:21] offset:16
	global_load_dwordx4 v[204:207], v149, s[20:21] offset:512
	global_load_dwordx4 v[208:211], v149, s[20:21] offset:528
	global_load_dwordx4 v[212:215], v148, s[74:75]
	global_load_dwordx4 v[216:219], v148, s[74:75] offset:256
	v_add_u32_e32 v151, 0x10000, v148
	global_load_dwordx4 v[220:223], v151, s[74:75]
	global_load_dwordx4 v[224:227], v151, s[74:75] offset:256
	v_add_u32_e32 v151, 0x20000, v148
	global_load_dwordx4 v[164:167], v151, s[74:75]
	global_load_dwordx4 v[168:171], v151, s[74:75] offset:256
	v_add_u32_e32 v151, 0x30000, v148
	global_load_dwordx4 v[172:175], v151, s[74:75]
	global_load_dwordx4 v[176:179], v151, s[74:75] offset:256
	s_waitcnt vmcnt(0)
	v_lshlrev_b32_e32 v180, 16, v212
	v_and_b32_e32 v181, 0xffff0000, v212
	v_lshlrev_b32_e32 v182, 16, v213
	v_and_b32_e32 v183, 0xffff0000, v213
	v_lshlrev_b32_e32 v184, 16, v214
	v_and_b32_e32 v185, 0xffff0000, v214
	v_lshlrev_b32_e32 v186, 16, v215
	v_and_b32_e32 v187, 0xffff0000, v215
	v_pk_fma_f32 v[124:125], v[124:125], v[196:197], v[180:181]
	v_pk_fma_f32 v[126:127], v[126:127], v[198:199], v[182:183]
	v_pk_fma_f32 v[120:121], v[120:121], v[200:201], v[184:185]
	v_pk_fma_f32 v[122:123], v[122:123], v[202:203], v[186:187]
	v_cvt_pk_bf16_f32 v123, v122, v123
	v_cvt_pk_bf16_f32 v122, v120, v121
	v_cvt_pk_bf16_f32 v121, v126, v127
	v_cvt_pk_bf16_f32 v120, v124, v125
	global_store_dwordx4 v148, v[120:123], s[74:75]
	v_lshlrev_b32_e32 v180, 16, v216
	v_and_b32_e32 v181, 0xffff0000, v216
	v_lshlrev_b32_e32 v182, 16, v217
	v_and_b32_e32 v183, 0xffff0000, v217
	v_lshlrev_b32_e32 v184, 16, v218
	v_and_b32_e32 v185, 0xffff0000, v218
	v_lshlrev_b32_e32 v186, 16, v219
	v_and_b32_e32 v187, 0xffff0000, v219
	v_pk_fma_f32 v[116:117], v[116:117], v[204:205], v[180:181]
	v_pk_fma_f32 v[118:119], v[118:119], v[206:207], v[182:183]
	v_pk_fma_f32 v[112:113], v[112:113], v[208:209], v[184:185]
	v_pk_fma_f32 v[114:115], v[114:115], v[210:211], v[186:187]
	v_cvt_pk_bf16_f32 v115, v114, v115
	v_cvt_pk_bf16_f32 v114, v112, v113
	v_cvt_pk_bf16_f32 v113, v118, v119
	v_cvt_pk_bf16_f32 v112, v116, v117
	global_store_dwordx4 v148, v[112:115], s[74:75] offset:256
	v_lshlrev_b32_e32 v180, 16, v220
	v_and_b32_e32 v181, 0xffff0000, v220
	v_lshlrev_b32_e32 v182, 16, v221
	v_and_b32_e32 v183, 0xffff0000, v221
	v_lshlrev_b32_e32 v184, 16, v222
	v_and_b32_e32 v185, 0xffff0000, v222
	v_lshlrev_b32_e32 v186, 16, v223
	v_and_b32_e32 v187, 0xffff0000, v223
	v_pk_fma_f32 v[108:109], v[108:109], v[196:197], v[180:181]
	v_pk_fma_f32 v[110:111], v[110:111], v[198:199], v[182:183]
	v_pk_fma_f32 v[104:105], v[104:105], v[200:201], v[184:185]
	v_pk_fma_f32 v[106:107], v[106:107], v[202:203], v[186:187]
	v_cvt_pk_bf16_f32 v107, v106, v107
	v_cvt_pk_bf16_f32 v106, v104, v105
	v_cvt_pk_bf16_f32 v105, v110, v111
	v_cvt_pk_bf16_f32 v104, v108, v109
	v_add_u32_e32 v151, 0x10000, v148
	global_store_dwordx4 v151, v[104:107], s[74:75]
	v_lshlrev_b32_e32 v180, 16, v224
	v_and_b32_e32 v181, 0xffff0000, v224
	v_lshlrev_b32_e32 v182, 16, v225
	v_and_b32_e32 v183, 0xffff0000, v225
	v_lshlrev_b32_e32 v184, 16, v226
	v_and_b32_e32 v185, 0xffff0000, v226
	v_lshlrev_b32_e32 v186, 16, v227
	v_and_b32_e32 v187, 0xffff0000, v227
	v_pk_fma_f32 v[100:101], v[100:101], v[204:205], v[180:181]
	v_pk_fma_f32 v[102:103], v[102:103], v[206:207], v[182:183]
	v_pk_fma_f32 v[96:97], v[96:97], v[208:209], v[184:185]
	v_pk_fma_f32 v[98:99], v[98:99], v[210:211], v[186:187]
	v_cvt_pk_bf16_f32 v99, v98, v99
	v_cvt_pk_bf16_f32 v98, v96, v97
	v_cvt_pk_bf16_f32 v97, v102, v103
	v_cvt_pk_bf16_f32 v96, v100, v101
	v_add_u32_e32 v151, 0x10000, v148
	global_store_dwordx4 v151, v[96:99], s[74:75] offset:256
	v_add_u32_e32 v151, 0x80000, v148
	global_load_dwordx4 v[212:215], v151, s[74:75]
	global_load_dwordx4 v[216:219], v151, s[74:75] offset:256
	v_add_u32_e32 v151, 0x90000, v148
	global_load_dwordx4 v[220:223], v151, s[74:75]
	global_load_dwordx4 v[224:227], v151, s[74:75] offset:256
	v_lshlrev_b32_e32 v180, 16, v164
	v_and_b32_e32 v181, 0xffff0000, v164
	v_lshlrev_b32_e32 v182, 16, v165
	v_and_b32_e32 v183, 0xffff0000, v165
	v_lshlrev_b32_e32 v184, 16, v166
	v_and_b32_e32 v185, 0xffff0000, v166
	v_lshlrev_b32_e32 v186, 16, v167
	v_and_b32_e32 v187, 0xffff0000, v167
	v_pk_fma_f32 v[92:93], v[92:93], v[196:197], v[180:181]
	v_pk_fma_f32 v[94:95], v[94:95], v[198:199], v[182:183]
	v_pk_fma_f32 v[88:89], v[88:89], v[200:201], v[184:185]
	v_pk_fma_f32 v[90:91], v[90:91], v[202:203], v[186:187]
	v_cvt_pk_bf16_f32 v91, v90, v91
	v_cvt_pk_bf16_f32 v90, v88, v89
	v_cvt_pk_bf16_f32 v89, v94, v95
	v_cvt_pk_bf16_f32 v88, v92, v93
	v_add_u32_e32 v151, 0x20000, v148
	global_store_dwordx4 v151, v[88:91], s[74:75]
	v_lshlrev_b32_e32 v180, 16, v168
	v_and_b32_e32 v181, 0xffff0000, v168
	v_lshlrev_b32_e32 v182, 16, v169
	v_and_b32_e32 v183, 0xffff0000, v169
	v_lshlrev_b32_e32 v184, 16, v170
	v_and_b32_e32 v185, 0xffff0000, v170
	v_lshlrev_b32_e32 v186, 16, v171
	v_and_b32_e32 v187, 0xffff0000, v171
	v_pk_fma_f32 v[84:85], v[84:85], v[204:205], v[180:181]
	v_pk_fma_f32 v[86:87], v[86:87], v[206:207], v[182:183]
	v_pk_fma_f32 v[80:81], v[80:81], v[208:209], v[184:185]
	v_pk_fma_f32 v[82:83], v[82:83], v[210:211], v[186:187]
	v_cvt_pk_bf16_f32 v83, v82, v83
	v_cvt_pk_bf16_f32 v82, v80, v81
	v_cvt_pk_bf16_f32 v81, v86, v87
	v_cvt_pk_bf16_f32 v80, v84, v85
	v_add_u32_e32 v151, 0x20000, v148
	global_store_dwordx4 v151, v[80:83], s[74:75] offset:256
	v_lshlrev_b32_e32 v180, 16, v172
	v_and_b32_e32 v181, 0xffff0000, v172
	v_lshlrev_b32_e32 v182, 16, v173
	v_and_b32_e32 v183, 0xffff0000, v173
	v_lshlrev_b32_e32 v184, 16, v174
	v_and_b32_e32 v185, 0xffff0000, v174
	v_lshlrev_b32_e32 v186, 16, v175
	v_and_b32_e32 v187, 0xffff0000, v175
	v_pk_fma_f32 v[76:77], v[76:77], v[196:197], v[180:181]
	v_pk_fma_f32 v[78:79], v[78:79], v[198:199], v[182:183]
	v_pk_fma_f32 v[72:73], v[72:73], v[200:201], v[184:185]
	v_pk_fma_f32 v[74:75], v[74:75], v[202:203], v[186:187]
	v_cvt_pk_bf16_f32 v75, v74, v75
	v_cvt_pk_bf16_f32 v74, v72, v73
	v_cvt_pk_bf16_f32 v73, v78, v79
	v_cvt_pk_bf16_f32 v72, v76, v77
	v_add_u32_e32 v151, 0x30000, v148
	global_store_dwordx4 v151, v[72:75], s[74:75]
	v_lshlrev_b32_e32 v180, 16, v176
	v_and_b32_e32 v181, 0xffff0000, v176
	v_lshlrev_b32_e32 v182, 16, v177
	v_and_b32_e32 v183, 0xffff0000, v177
	v_lshlrev_b32_e32 v184, 16, v178
	v_and_b32_e32 v185, 0xffff0000, v178
	v_lshlrev_b32_e32 v186, 16, v179
	v_and_b32_e32 v187, 0xffff0000, v179
	v_pk_fma_f32 v[68:69], v[68:69], v[204:205], v[180:181]
	v_pk_fma_f32 v[70:71], v[70:71], v[206:207], v[182:183]
	v_pk_fma_f32 v[64:65], v[64:65], v[208:209], v[184:185]
	v_pk_fma_f32 v[66:67], v[66:67], v[210:211], v[186:187]
	v_cvt_pk_bf16_f32 v67, v66, v67
	v_cvt_pk_bf16_f32 v66, v64, v65
	v_cvt_pk_bf16_f32 v65, v70, v71
	v_cvt_pk_bf16_f32 v64, v68, v69
	v_add_u32_e32 v151, 0x30000, v148
	global_store_dwordx4 v151, v[64:67], s[74:75] offset:256
	v_add_u32_e32 v151, 0xa0000, v148
	global_load_dwordx4 v[164:167], v151, s[74:75]
	global_load_dwordx4 v[168:171], v151, s[74:75] offset:256
	v_add_u32_e32 v151, 0xb0000, v148
	global_load_dwordx4 v[172:175], v151, s[74:75]
	global_load_dwordx4 v[176:179], v151, s[74:75] offset:256
	s_waitcnt vmcnt(0)
	v_lshlrev_b32_e32 v180, 16, v212
	v_and_b32_e32 v181, 0xffff0000, v212
	v_lshlrev_b32_e32 v182, 16, v213
	v_and_b32_e32 v183, 0xffff0000, v213
	v_lshlrev_b32_e32 v184, 16, v214
	v_and_b32_e32 v185, 0xffff0000, v214
	v_lshlrev_b32_e32 v186, 16, v215
	v_and_b32_e32 v187, 0xffff0000, v215
	v_pk_fma_f32 v[60:61], v[60:61], v[196:197], v[180:181]
	v_pk_fma_f32 v[62:63], v[62:63], v[198:199], v[182:183]
	v_pk_fma_f32 v[56:57], v[56:57], v[200:201], v[184:185]
	v_pk_fma_f32 v[58:59], v[58:59], v[202:203], v[186:187]
	v_cvt_pk_bf16_f32 v59, v58, v59
	v_cvt_pk_bf16_f32 v58, v56, v57
	v_cvt_pk_bf16_f32 v57, v62, v63
	v_cvt_pk_bf16_f32 v56, v60, v61
	v_add_u32_e32 v151, 0x80000, v148
	global_store_dwordx4 v151, v[56:59], s[74:75]
	v_lshlrev_b32_e32 v180, 16, v216
	v_and_b32_e32 v181, 0xffff0000, v216
	v_lshlrev_b32_e32 v182, 16, v217
	v_and_b32_e32 v183, 0xffff0000, v217
	v_lshlrev_b32_e32 v184, 16, v218
	v_and_b32_e32 v185, 0xffff0000, v218
	v_lshlrev_b32_e32 v186, 16, v219
	v_and_b32_e32 v187, 0xffff0000, v219
	v_pk_fma_f32 v[52:53], v[52:53], v[204:205], v[180:181]
	v_pk_fma_f32 v[54:55], v[54:55], v[206:207], v[182:183]
	v_pk_fma_f32 v[48:49], v[48:49], v[208:209], v[184:185]
	v_pk_fma_f32 v[50:51], v[50:51], v[210:211], v[186:187]
	v_cvt_pk_bf16_f32 v51, v50, v51
	v_cvt_pk_bf16_f32 v50, v48, v49
	v_cvt_pk_bf16_f32 v49, v54, v55
	v_cvt_pk_bf16_f32 v48, v52, v53
	v_add_u32_e32 v151, 0x80000, v148
	global_store_dwordx4 v151, v[48:51], s[74:75] offset:256
	v_lshlrev_b32_e32 v180, 16, v220
	v_and_b32_e32 v181, 0xffff0000, v220
	v_lshlrev_b32_e32 v182, 16, v221
	v_and_b32_e32 v183, 0xffff0000, v221
	v_lshlrev_b32_e32 v184, 16, v222
	v_and_b32_e32 v185, 0xffff0000, v222
	v_lshlrev_b32_e32 v186, 16, v223
	v_and_b32_e32 v187, 0xffff0000, v223
	v_pk_fma_f32 v[44:45], v[44:45], v[196:197], v[180:181]
	v_pk_fma_f32 v[46:47], v[46:47], v[198:199], v[182:183]
	v_pk_fma_f32 v[40:41], v[40:41], v[200:201], v[184:185]
	v_pk_fma_f32 v[42:43], v[42:43], v[202:203], v[186:187]
	v_cvt_pk_bf16_f32 v43, v42, v43
	v_cvt_pk_bf16_f32 v42, v40, v41
	v_cvt_pk_bf16_f32 v41, v46, v47
	v_cvt_pk_bf16_f32 v40, v44, v45
	v_add_u32_e32 v151, 0x90000, v148
	global_store_dwordx4 v151, v[40:43], s[74:75]
	v_lshlrev_b32_e32 v180, 16, v224
	v_and_b32_e32 v181, 0xffff0000, v224
	v_lshlrev_b32_e32 v182, 16, v225
	v_and_b32_e32 v183, 0xffff0000, v225
	v_lshlrev_b32_e32 v184, 16, v226
	v_and_b32_e32 v185, 0xffff0000, v226
	v_lshlrev_b32_e32 v186, 16, v227
	v_and_b32_e32 v187, 0xffff0000, v227
	v_pk_fma_f32 v[36:37], v[36:37], v[204:205], v[180:181]
	v_pk_fma_f32 v[38:39], v[38:39], v[206:207], v[182:183]
	v_pk_fma_f32 v[32:33], v[32:33], v[208:209], v[184:185]
	v_pk_fma_f32 v[34:35], v[34:35], v[210:211], v[186:187]
	v_cvt_pk_bf16_f32 v35, v34, v35
	v_cvt_pk_bf16_f32 v34, v32, v33
	v_cvt_pk_bf16_f32 v33, v38, v39
	v_cvt_pk_bf16_f32 v32, v36, v37
	v_add_u32_e32 v151, 0x90000, v148
	global_store_dwordx4 v151, v[32:35], s[74:75] offset:256
	v_lshlrev_b32_e32 v180, 16, v164
	v_and_b32_e32 v181, 0xffff0000, v164
	v_lshlrev_b32_e32 v182, 16, v165
	v_and_b32_e32 v183, 0xffff0000, v165
	v_lshlrev_b32_e32 v184, 16, v166
	v_and_b32_e32 v185, 0xffff0000, v166
	v_lshlrev_b32_e32 v186, 16, v167
	v_and_b32_e32 v187, 0xffff0000, v167
	v_pk_fma_f32 v[28:29], v[28:29], v[196:197], v[180:181]
	v_pk_fma_f32 v[30:31], v[30:31], v[198:199], v[182:183]
	v_pk_fma_f32 v[24:25], v[24:25], v[200:201], v[184:185]
	v_pk_fma_f32 v[26:27], v[26:27], v[202:203], v[186:187]
	v_cvt_pk_bf16_f32 v27, v26, v27
	v_cvt_pk_bf16_f32 v26, v24, v25
	v_cvt_pk_bf16_f32 v25, v30, v31
	v_cvt_pk_bf16_f32 v24, v28, v29
	v_add_u32_e32 v151, 0xa0000, v148
	global_store_dwordx4 v151, v[24:27], s[74:75]
	v_lshlrev_b32_e32 v180, 16, v168
	v_and_b32_e32 v181, 0xffff0000, v168
	v_lshlrev_b32_e32 v182, 16, v169
	v_and_b32_e32 v183, 0xffff0000, v169
	v_lshlrev_b32_e32 v184, 16, v170
	v_and_b32_e32 v185, 0xffff0000, v170
	v_lshlrev_b32_e32 v186, 16, v171
	v_and_b32_e32 v187, 0xffff0000, v171
	v_pk_fma_f32 v[20:21], v[20:21], v[204:205], v[180:181]
	v_pk_fma_f32 v[22:23], v[22:23], v[206:207], v[182:183]
	v_pk_fma_f32 v[16:17], v[16:17], v[208:209], v[184:185]
	v_pk_fma_f32 v[18:19], v[18:19], v[210:211], v[186:187]
	v_cvt_pk_bf16_f32 v19, v18, v19
	v_cvt_pk_bf16_f32 v18, v16, v17
	v_cvt_pk_bf16_f32 v17, v22, v23
	v_cvt_pk_bf16_f32 v16, v20, v21
	v_add_u32_e32 v151, 0xa0000, v148
	global_store_dwordx4 v151, v[16:19], s[74:75] offset:256
	v_lshlrev_b32_e32 v180, 16, v172
	v_and_b32_e32 v181, 0xffff0000, v172
	v_lshlrev_b32_e32 v182, 16, v173
	v_and_b32_e32 v183, 0xffff0000, v173
	v_lshlrev_b32_e32 v184, 16, v174
	v_and_b32_e32 v185, 0xffff0000, v174
	v_lshlrev_b32_e32 v186, 16, v175
	v_and_b32_e32 v187, 0xffff0000, v175
	v_pk_fma_f32 v[12:13], v[12:13], v[196:197], v[180:181]
	v_pk_fma_f32 v[14:15], v[14:15], v[198:199], v[182:183]
	v_pk_fma_f32 v[8:9], v[8:9], v[200:201], v[184:185]
	v_pk_fma_f32 v[10:11], v[10:11], v[202:203], v[186:187]
	v_cvt_pk_bf16_f32 v11, v10, v11
	v_cvt_pk_bf16_f32 v10, v8, v9
	v_cvt_pk_bf16_f32 v9, v14, v15
	v_cvt_pk_bf16_f32 v8, v12, v13
	v_add_u32_e32 v151, 0xb0000, v148
	global_store_dwordx4 v151, v[8:11], s[74:75]
	v_lshlrev_b32_e32 v180, 16, v176
	v_and_b32_e32 v181, 0xffff0000, v176
	v_lshlrev_b32_e32 v182, 16, v177
	v_and_b32_e32 v183, 0xffff0000, v177
	v_lshlrev_b32_e32 v184, 16, v178
	v_and_b32_e32 v185, 0xffff0000, v178
	v_lshlrev_b32_e32 v186, 16, v179
	v_and_b32_e32 v187, 0xffff0000, v179
	v_pk_fma_f32 v[4:5], v[4:5], v[204:205], v[180:181]
	v_pk_fma_f32 v[6:7], v[6:7], v[206:207], v[182:183]
	v_pk_fma_f32 v[0:1], v[0:1], v[208:209], v[184:185]
	v_pk_fma_f32 v[2:3], v[2:3], v[210:211], v[186:187]
	v_cvt_pk_bf16_f32 v3, v2, v3
	v_cvt_pk_bf16_f32 v2, v0, v1
	v_cvt_pk_bf16_f32 v1, v6, v7
	v_cvt_pk_bf16_f32 v0, v4, v5
	v_add_u32_e32 v151, 0xb0000, v148
	global_store_dwordx4 v151, v[0:3], s[74:75] offset:256
.Lepi_nl_c_out:
	s_cmp_gt_u32 s61, 29
	s_barrier
	s_cbranch_scc0 .LBB0_1346
	s_cmp_lg_u32 s51, 0
	s_cbranch_scc1 .Lepi_g0done_c_out
	s_lshl_b32 s15, s36, 8
	s_add_i32 s15, s15, s51
	v_or_b32_e32 v154, s15, v145
	s_add_i32 s17, s15, 0xffffe000
	v_lshl_or_b32 v150, s33, 8, v157
	s_lshr_b32 s17, s17, 12
	v_lshlrev_b32_e32 v148, 12, v154
	s_add_i32 s17, s17, 1
	s_cmp_gt_i32 s15, s56
	s_cselect_b32 s17, s17, 0
	s_mul_i32 s17, s17, s54
	v_lshl_add_u32 v148, v150, 1, v148
	s_add_u32 s20, s8, s17
	s_addc_u32 s21, s9, 0
	v_lshlrev_b32_e32 v149, 2, v150
	s_nop 0
	global_load_dwordx4 v[196:199], v149, s[20:21]
	global_load_dwordx4 v[200:203], v149, s[20:21] offset:16
	global_load_dwordx4 v[204:207], v149, s[20:21] offset:512
	global_load_dwordx4 v[208:211], v149, s[20:21] offset:528
	global_load_dwordx4 v[212:215], v148, s[74:75]
	global_load_dwordx4 v[216:219], v148, s[74:75] offset:256
	v_add_u32_e32 v151, 0x10000, v148
	global_load_dwordx4 v[220:223], v151, s[74:75]
	global_load_dwordx4 v[224:227], v151, s[74:75] offset:256
	v_add_u32_e32 v151, 0x20000, v148
	global_load_dwordx4 v[164:167], v151, s[74:75]
	global_load_dwordx4 v[168:171], v151, s[74:75] offset:256
	v_add_u32_e32 v151, 0x30000, v148
	global_load_dwordx4 v[172:175], v151, s[74:75]
	global_load_dwordx4 v[176:179], v151, s[74:75] offset:256
	s_waitcnt vmcnt(0)
	v_lshlrev_b32_e32 v180, 16, v212
	v_and_b32_e32 v181, 0xffff0000, v212
	v_lshlrev_b32_e32 v182, 16, v213
	v_and_b32_e32 v183, 0xffff0000, v213
	v_lshlrev_b32_e32 v184, 16, v214
	v_and_b32_e32 v185, 0xffff0000, v214
	v_lshlrev_b32_e32 v186, 16, v215
	v_and_b32_e32 v187, 0xffff0000, v215
	v_pk_fma_f32 v[124:125], v[124:125], v[196:197], v[180:181]
	v_pk_fma_f32 v[126:127], v[126:127], v[198:199], v[182:183]
	v_pk_fma_f32 v[120:121], v[120:121], v[200:201], v[184:185]
	v_pk_fma_f32 v[122:123], v[122:123], v[202:203], v[186:187]
	v_cvt_pk_bf16_f32 v123, v122, v123
	v_cvt_pk_bf16_f32 v122, v120, v121
	v_cvt_pk_bf16_f32 v121, v126, v127
	v_cvt_pk_bf16_f32 v120, v124, v125
	global_store_dwordx4 v148, v[120:123], s[74:75]
	v_lshlrev_b32_e32 v180, 16, v216
	v_and_b32_e32 v181, 0xffff0000, v216
	v_lshlrev_b32_e32 v182, 16, v217
	v_and_b32_e32 v183, 0xffff0000, v217
	v_lshlrev_b32_e32 v184, 16, v218
	v_and_b32_e32 v185, 0xffff0000, v218
	v_lshlrev_b32_e32 v186, 16, v219
	v_and_b32_e32 v187, 0xffff0000, v219
	v_pk_fma_f32 v[116:117], v[116:117], v[204:205], v[180:181]
	v_pk_fma_f32 v[118:119], v[118:119], v[206:207], v[182:183]
	v_pk_fma_f32 v[112:113], v[112:113], v[208:209], v[184:185]
	v_pk_fma_f32 v[114:115], v[114:115], v[210:211], v[186:187]
	v_cvt_pk_bf16_f32 v115, v114, v115
	v_cvt_pk_bf16_f32 v114, v112, v113
	v_cvt_pk_bf16_f32 v113, v118, v119
	v_cvt_pk_bf16_f32 v112, v116, v117
	global_store_dwordx4 v148, v[112:115], s[74:75] offset:256
	v_lshlrev_b32_e32 v180, 16, v220
	v_and_b32_e32 v181, 0xffff0000, v220
	v_lshlrev_b32_e32 v182, 16, v221
	v_and_b32_e32 v183, 0xffff0000, v221
	v_lshlrev_b32_e32 v184, 16, v222
	v_and_b32_e32 v185, 0xffff0000, v222
	v_lshlrev_b32_e32 v186, 16, v223
	v_and_b32_e32 v187, 0xffff0000, v223
	v_pk_fma_f32 v[108:109], v[108:109], v[196:197], v[180:181]
	v_pk_fma_f32 v[110:111], v[110:111], v[198:199], v[182:183]
	v_pk_fma_f32 v[104:105], v[104:105], v[200:201], v[184:185]
	v_pk_fma_f32 v[106:107], v[106:107], v[202:203], v[186:187]
	v_cvt_pk_bf16_f32 v107, v106, v107
	v_cvt_pk_bf16_f32 v106, v104, v105
	v_cvt_pk_bf16_f32 v105, v110, v111
	v_cvt_pk_bf16_f32 v104, v108, v109
	v_add_u32_e32 v151, 0x10000, v148
	global_store_dwordx4 v151, v[104:107], s[74:75]
	v_lshlrev_b32_e32 v180, 16, v224
	v_and_b32_e32 v181, 0xffff0000, v224
	v_lshlrev_b32_e32 v182, 16, v225
	v_and_b32_e32 v183, 0xffff0000, v225
	v_lshlrev_b32_e32 v184, 16, v226
	v_and_b32_e32 v185, 0xffff0000, v226
	v_lshlrev_b32_e32 v186, 16, v227
	v_and_b32_e32 v187, 0xffff0000, v227
	v_pk_fma_f32 v[100:101], v[100:101], v[204:205], v[180:181]
	v_pk_fma_f32 v[102:103], v[102:103], v[206:207], v[182:183]
	v_pk_fma_f32 v[96:97], v[96:97], v[208:209], v[184:185]
	v_pk_fma_f32 v[98:99], v[98:99], v[210:211], v[186:187]
	v_cvt_pk_bf16_f32 v99, v98, v99
	v_cvt_pk_bf16_f32 v98, v96, v97
	v_cvt_pk_bf16_f32 v97, v102, v103
	v_cvt_pk_bf16_f32 v96, v100, v101
	v_add_u32_e32 v151, 0x10000, v148
	global_store_dwordx4 v151, v[96:99], s[74:75] offset:256
	v_add_u32_e32 v151, 0x80000, v148
	global_load_dwordx4 v[212:215], v151, s[74:75]
	global_load_dwordx4 v[216:219], v151, s[74:75] offset:256
	v_add_u32_e32 v151, 0x90000, v148
	global_load_dwordx4 v[220:223], v151, s[74:75]
	global_load_dwordx4 v[224:227], v151, s[74:75] offset:256
	v_lshlrev_b32_e32 v180, 16, v164
	v_and_b32_e32 v181, 0xffff0000, v164
	v_lshlrev_b32_e32 v182, 16, v165
	v_and_b32_e32 v183, 0xffff0000, v165
	v_lshlrev_b32_e32 v184, 16, v166
	v_and_b32_e32 v185, 0xffff0000, v166
	v_lshlrev_b32_e32 v186, 16, v167
	v_and_b32_e32 v187, 0xffff0000, v167
	v_pk_fma_f32 v[92:93], v[92:93], v[196:197], v[180:181]
	v_pk_fma_f32 v[94:95], v[94:95], v[198:199], v[182:183]
	v_pk_fma_f32 v[88:89], v[88:89], v[200:201], v[184:185]
	v_pk_fma_f32 v[90:91], v[90:91], v[202:203], v[186:187]
	v_cvt_pk_bf16_f32 v91, v90, v91
	v_cvt_pk_bf16_f32 v90, v88, v89
	v_cvt_pk_bf16_f32 v89, v94, v95
	v_cvt_pk_bf16_f32 v88, v92, v93
	v_add_u32_e32 v151, 0x20000, v148
	global_store_dwordx4 v151, v[88:91], s[74:75]
	v_lshlrev_b32_e32 v180, 16, v168
	v_and_b32_e32 v181, 0xffff0000, v168
	v_lshlrev_b32_e32 v182, 16, v169
	v_and_b32_e32 v183, 0xffff0000, v169
	v_lshlrev_b32_e32 v184, 16, v170
	v_and_b32_e32 v185, 0xffff0000, v170
	v_lshlrev_b32_e32 v186, 16, v171
	v_and_b32_e32 v187, 0xffff0000, v171
	v_pk_fma_f32 v[84:85], v[84:85], v[204:205], v[180:181]
	v_pk_fma_f32 v[86:87], v[86:87], v[206:207], v[182:183]
	v_pk_fma_f32 v[80:81], v[80:81], v[208:209], v[184:185]
	v_pk_fma_f32 v[82:83], v[82:83], v[210:211], v[186:187]
	v_cvt_pk_bf16_f32 v83, v82, v83
	v_cvt_pk_bf16_f32 v82, v80, v81
	v_cvt_pk_bf16_f32 v81, v86, v87
	v_cvt_pk_bf16_f32 v80, v84, v85
	v_add_u32_e32 v151, 0x20000, v148
	global_store_dwordx4 v151, v[80:83], s[74:75] offset:256
	v_lshlrev_b32_e32 v180, 16, v172
	v_and_b32_e32 v181, 0xffff0000, v172
	v_lshlrev_b32_e32 v182, 16, v173
	v_and_b32_e32 v183, 0xffff0000, v173
	v_lshlrev_b32_e32 v184, 16, v174
	v_and_b32_e32 v185, 0xffff0000, v174
	v_lshlrev_b32_e32 v186, 16, v175
	v_and_b32_e32 v187, 0xffff0000, v175
	v_pk_fma_f32 v[76:77], v[76:77], v[196:197], v[180:181]
	v_pk_fma_f32 v[78:79], v[78:79], v[198:199], v[182:183]
	v_pk_fma_f32 v[72:73], v[72:73], v[200:201], v[184:185]
	v_pk_fma_f32 v[74:75], v[74:75], v[202:203], v[186:187]
	v_cvt_pk_bf16_f32 v75, v74, v75
	v_cvt_pk_bf16_f32 v74, v72, v73
	v_cvt_pk_bf16_f32 v73, v78, v79
	v_cvt_pk_bf16_f32 v72, v76, v77
	v_add_u32_e32 v151, 0x30000, v148
	global_store_dwordx4 v151, v[72:75], s[74:75]
	v_lshlrev_b32_e32 v180, 16, v176
	v_and_b32_e32 v181, 0xffff0000, v176
	v_lshlrev_b32_e32 v182, 16, v177
	v_and_b32_e32 v183, 0xffff0000, v177
	v_lshlrev_b32_e32 v184, 16, v178
	v_and_b32_e32 v185, 0xffff0000, v178
	v_lshlrev_b32_e32 v186, 16, v179
	v_and_b32_e32 v187, 0xffff0000, v179
	v_pk_fma_f32 v[68:69], v[68:69], v[204:205], v[180:181]
	v_pk_fma_f32 v[70:71], v[70:71], v[206:207], v[182:183]
	v_pk_fma_f32 v[64:65], v[64:65], v[208:209], v[184:185]
	v_pk_fma_f32 v[66:67], v[66:67], v[210:211], v[186:187]
	v_cvt_pk_bf16_f32 v67, v66, v67
	v_cvt_pk_bf16_f32 v66, v64, v65
	v_cvt_pk_bf16_f32 v65, v70, v71
	v_cvt_pk_bf16_f32 v64, v68, v69
	v_add_u32_e32 v151, 0x30000, v148
	global_store_dwordx4 v151, v[64:67], s[74:75] offset:256
	v_add_u32_e32 v151, 0xa0000, v148
	global_load_dwordx4 v[164:167], v151, s[74:75]
	global_load_dwordx4 v[168:171], v151, s[74:75] offset:256
	v_add_u32_e32 v151, 0xb0000, v148
	global_load_dwordx4 v[172:175], v151, s[74:75]
	global_load_dwordx4 v[176:179], v151, s[74:75] offset:256
	s_waitcnt vmcnt(0)
	v_lshlrev_b32_e32 v180, 16, v212
	v_and_b32_e32 v181, 0xffff0000, v212
	v_lshlrev_b32_e32 v182, 16, v213
	v_and_b32_e32 v183, 0xffff0000, v213
	v_lshlrev_b32_e32 v184, 16, v214
	v_and_b32_e32 v185, 0xffff0000, v214
	v_lshlrev_b32_e32 v186, 16, v215
	v_and_b32_e32 v187, 0xffff0000, v215
	v_pk_fma_f32 v[60:61], v[60:61], v[196:197], v[180:181]
	v_pk_fma_f32 v[62:63], v[62:63], v[198:199], v[182:183]
	v_pk_fma_f32 v[56:57], v[56:57], v[200:201], v[184:185]
	v_pk_fma_f32 v[58:59], v[58:59], v[202:203], v[186:187]
	v_cvt_pk_bf16_f32 v59, v58, v59
	v_cvt_pk_bf16_f32 v58, v56, v57
	v_cvt_pk_bf16_f32 v57, v62, v63
	v_cvt_pk_bf16_f32 v56, v60, v61
	v_add_u32_e32 v151, 0x80000, v148
	global_store_dwordx4 v151, v[56:59], s[74:75]
	v_lshlrev_b32_e32 v180, 16, v216
	v_and_b32_e32 v181, 0xffff0000, v216
	v_lshlrev_b32_e32 v182, 16, v217
	v_and_b32_e32 v183, 0xffff0000, v217
	v_lshlrev_b32_e32 v184, 16, v218
	v_and_b32_e32 v185, 0xffff0000, v218
	v_lshlrev_b32_e32 v186, 16, v219
	v_and_b32_e32 v187, 0xffff0000, v219
	v_pk_fma_f32 v[52:53], v[52:53], v[204:205], v[180:181]
	v_pk_fma_f32 v[54:55], v[54:55], v[206:207], v[182:183]
	v_pk_fma_f32 v[48:49], v[48:49], v[208:209], v[184:185]
	v_pk_fma_f32 v[50:51], v[50:51], v[210:211], v[186:187]
	v_cvt_pk_bf16_f32 v51, v50, v51
	v_cvt_pk_bf16_f32 v50, v48, v49
	v_cvt_pk_bf16_f32 v49, v54, v55
	v_cvt_pk_bf16_f32 v48, v52, v53
	v_add_u32_e32 v151, 0x80000, v148
	global_store_dwordx4 v151, v[48:51], s[74:75] offset:256
	v_lshlrev_b32_e32 v180, 16, v220
	v_and_b32_e32 v181, 0xffff0000, v220
	v_lshlrev_b32_e32 v182, 16, v221
	v_and_b32_e32 v183, 0xffff0000, v221
	v_lshlrev_b32_e32 v184, 16, v222
	v_and_b32_e32 v185, 0xffff0000, v222
	v_lshlrev_b32_e32 v186, 16, v223
	v_and_b32_e32 v187, 0xffff0000, v223
	v_pk_fma_f32 v[44:45], v[44:45], v[196:197], v[180:181]
	v_pk_fma_f32 v[46:47], v[46:47], v[198:199], v[182:183]
	v_pk_fma_f32 v[40:41], v[40:41], v[200:201], v[184:185]
	v_pk_fma_f32 v[42:43], v[42:43], v[202:203], v[186:187]
	v_cvt_pk_bf16_f32 v43, v42, v43
	v_cvt_pk_bf16_f32 v42, v40, v41
	v_cvt_pk_bf16_f32 v41, v46, v47
	v_cvt_pk_bf16_f32 v40, v44, v45
	v_add_u32_e32 v151, 0x90000, v148
	global_store_dwordx4 v151, v[40:43], s[74:75]
	v_lshlrev_b32_e32 v180, 16, v224
	v_and_b32_e32 v181, 0xffff0000, v224
	v_lshlrev_b32_e32 v182, 16, v225
	v_and_b32_e32 v183, 0xffff0000, v225
	v_lshlrev_b32_e32 v184, 16, v226
	v_and_b32_e32 v185, 0xffff0000, v226
	v_lshlrev_b32_e32 v186, 16, v227
	v_and_b32_e32 v187, 0xffff0000, v227
	v_pk_fma_f32 v[36:37], v[36:37], v[204:205], v[180:181]
	v_pk_fma_f32 v[38:39], v[38:39], v[206:207], v[182:183]
	v_pk_fma_f32 v[32:33], v[32:33], v[208:209], v[184:185]
	v_pk_fma_f32 v[34:35], v[34:35], v[210:211], v[186:187]
	v_cvt_pk_bf16_f32 v35, v34, v35
	v_cvt_pk_bf16_f32 v34, v32, v33
	v_cvt_pk_bf16_f32 v33, v38, v39
	v_cvt_pk_bf16_f32 v32, v36, v37
	v_add_u32_e32 v151, 0x90000, v148
	global_store_dwordx4 v151, v[32:35], s[74:75] offset:256
	v_lshlrev_b32_e32 v180, 16, v164
	v_and_b32_e32 v181, 0xffff0000, v164
	v_lshlrev_b32_e32 v182, 16, v165
	v_and_b32_e32 v183, 0xffff0000, v165
	v_lshlrev_b32_e32 v184, 16, v166
	v_and_b32_e32 v185, 0xffff0000, v166
	v_lshlrev_b32_e32 v186, 16, v167
	v_and_b32_e32 v187, 0xffff0000, v167
	v_pk_fma_f32 v[28:29], v[28:29], v[196:197], v[180:181]
	v_pk_fma_f32 v[30:31], v[30:31], v[198:199], v[182:183]
	v_pk_fma_f32 v[24:25], v[24:25], v[200:201], v[184:185]
	v_pk_fma_f32 v[26:27], v[26:27], v[202:203], v[186:187]
	v_cvt_pk_bf16_f32 v27, v26, v27
	v_cvt_pk_bf16_f32 v26, v24, v25
	v_cvt_pk_bf16_f32 v25, v30, v31
	v_cvt_pk_bf16_f32 v24, v28, v29
	v_add_u32_e32 v151, 0xa0000, v148
	global_store_dwordx4 v151, v[24:27], s[74:75]
	v_lshlrev_b32_e32 v180, 16, v168
	v_and_b32_e32 v181, 0xffff0000, v168
	v_lshlrev_b32_e32 v182, 16, v169
	v_and_b32_e32 v183, 0xffff0000, v169
	v_lshlrev_b32_e32 v184, 16, v170
	v_and_b32_e32 v185, 0xffff0000, v170
	v_lshlrev_b32_e32 v186, 16, v171
	v_and_b32_e32 v187, 0xffff0000, v171
	v_pk_fma_f32 v[20:21], v[20:21], v[204:205], v[180:181]
	v_pk_fma_f32 v[22:23], v[22:23], v[206:207], v[182:183]
	v_pk_fma_f32 v[16:17], v[16:17], v[208:209], v[184:185]
	v_pk_fma_f32 v[18:19], v[18:19], v[210:211], v[186:187]
	v_cvt_pk_bf16_f32 v19, v18, v19
	v_cvt_pk_bf16_f32 v18, v16, v17
	v_cvt_pk_bf16_f32 v17, v22, v23
	v_cvt_pk_bf16_f32 v16, v20, v21
	v_add_u32_e32 v151, 0xa0000, v148
	global_store_dwordx4 v151, v[16:19], s[74:75] offset:256
	v_lshlrev_b32_e32 v180, 16, v172
	v_and_b32_e32 v181, 0xffff0000, v172
	v_lshlrev_b32_e32 v182, 16, v173
	v_and_b32_e32 v183, 0xffff0000, v173
	v_lshlrev_b32_e32 v184, 16, v174
	v_and_b32_e32 v185, 0xffff0000, v174
	v_lshlrev_b32_e32 v186, 16, v175
	v_and_b32_e32 v187, 0xffff0000, v175
	v_pk_fma_f32 v[12:13], v[12:13], v[196:197], v[180:181]
	v_pk_fma_f32 v[14:15], v[14:15], v[198:199], v[182:183]
	v_pk_fma_f32 v[8:9], v[8:9], v[200:201], v[184:185]
	v_pk_fma_f32 v[10:11], v[10:11], v[202:203], v[186:187]
	v_cvt_pk_bf16_f32 v11, v10, v11
	v_cvt_pk_bf16_f32 v10, v8, v9
	v_cvt_pk_bf16_f32 v9, v14, v15
	v_cvt_pk_bf16_f32 v8, v12, v13
	v_add_u32_e32 v151, 0xb0000, v148
	global_store_dwordx4 v151, v[8:11], s[74:75]
	v_lshlrev_b32_e32 v180, 16, v176
	v_and_b32_e32 v181, 0xffff0000, v176
	v_lshlrev_b32_e32 v182, 16, v177
	v_and_b32_e32 v183, 0xffff0000, v177
	v_lshlrev_b32_e32 v184, 16, v178
	v_and_b32_e32 v185, 0xffff0000, v178
	v_lshlrev_b32_e32 v186, 16, v179
	v_and_b32_e32 v187, 0xffff0000, v179
	v_pk_fma_f32 v[4:5], v[4:5], v[204:205], v[180:181]
	v_pk_fma_f32 v[6:7], v[6:7], v[206:207], v[182:183]
	v_pk_fma_f32 v[0:1], v[0:1], v[208:209], v[184:185]
	v_pk_fma_f32 v[2:3], v[2:3], v[210:211], v[186:187]
	v_cvt_pk_bf16_f32 v3, v2, v3
	v_cvt_pk_bf16_f32 v2, v0, v1
	v_cvt_pk_bf16_f32 v1, v6, v7
	v_cvt_pk_bf16_f32 v0, v4, v5
	v_add_u32_e32 v151, 0xb0000, v148
	global_store_dwordx4 v151, v[0:3], s[74:75] offset:256
.Lepi_g0done_c_out:
	s_mov_b32 s33, s14
	s_mov_b32 s36, s16
	s_mov_b64 s[44:45], s[24:25]
	s_mov_b64 s[38:39], s[18:19]
	s_and_b64 vcc, exec, s[0:1]
	s_cbranch_vccz .LBB0_1343
	s_waitcnt vmcnt(0)
	s_cmpk_gt_u32 s12, 0xff
	s_cbranch_scc1 .LBB0_1350
	s_barrier

.LBB0_1433:
	ds_read_b128 v[148:151], v158
	ds_read_b128 v[152:155], v158 offset:1024
	ds_read_b128 v[162:165], v158 offset:2048
	ds_read_b128 v[166:169], v158 offset:3072
	s_add_u32 s20, s26, 0xffe00080
	s_addc_u32 s21, s27, -1
	s_cmpk_eq_i32 s53, 0x7c
	s_cselect_b32 s21, s15, s21
	s_cselect_b32 s20, s49, s20
	s_cselect_b32 s31, s11, s52
	s_cselect_b32 s30, s50, s51
	v_lshl_add_u64 v[204:205], s[26:27], 0, v[136:137]
	s_add_i32 m0, s25, 0xc000
	ds_read_b128 v[170:173], v159
	ds_read_b128 v[174:177], v159 offset:1024
	ds_read_b128 v[178:181], v159 offset:2048
	ds_read_b128 v[182:185], v159 offset:3072
	ds_read_b128 v[186:189], v159 offset:4096
	ds_read_b128 v[190:193], v159 offset:5120
	ds_read_b128 v[196:199], v159 offset:6144
	ds_read_b128 v[200:203], v159 offset:7168
	global_load_lds_dwordx4 v[204:205], off
	v_lshl_add_u64 v[204:205], s[26:27], 0, v[138:139]
	s_add_i32 m0, s25, 0xe000
	s_nop 0
	global_load_lds_dwordx4 v[204:205], off
	s_waitcnt lgkmcnt(8)
	s_barrier
	s_waitcnt lgkmcnt(0)
	s_setprio 1
	s_waitcnt lgkmcnt(0)
	v_mfma_f32_16x16x32_bf16 v[124:127], v[148:151], v[170:173], v[124:127]
	v_mfma_f32_16x16x32_bf16 v[120:123], v[162:165], v[170:173], v[120:123]
	v_mfma_f32_16x16x32_bf16 v[108:111], v[148:151], v[178:181], v[108:111]
	v_mfma_f32_16x16x32_bf16 v[104:107], v[162:165], v[178:181], v[104:107]
	v_mfma_f32_16x16x32_bf16 v[92:95], v[148:151], v[186:189], v[92:95]
	v_mfma_f32_16x16x32_bf16 v[88:91], v[162:165], v[186:189], v[88:91]
	v_mfma_f32_16x16x32_bf16 v[76:79], v[148:151], v[196:199], v[76:79]
	v_mfma_f32_16x16x32_bf16 v[72:75], v[162:165], v[196:199], v[72:75]
	v_mfma_f32_16x16x32_bf16 v[124:127], v[152:155], v[174:177], v[124:127]
	v_mfma_f32_16x16x32_bf16 v[120:123], v[166:169], v[174:177], v[120:123]
	v_mfma_f32_16x16x32_bf16 v[108:111], v[152:155], v[182:185], v[108:111]
	v_mfma_f32_16x16x32_bf16 v[104:107], v[166:169], v[182:185], v[104:107]
	v_mfma_f32_16x16x32_bf16 v[92:95], v[152:155], v[190:193], v[92:95]
	v_mfma_f32_16x16x32_bf16 v[88:91], v[166:169], v[190:193], v[88:91]
	v_mfma_f32_16x16x32_bf16 v[76:79], v[152:155], v[200:203], v[76:79]
	v_mfma_f32_16x16x32_bf16 v[72:75], v[166:169], v[200:203], v[72:75]
	s_setprio 0
	s_barrier
	s_add_i32 s54, s45, s23
	v_lshl_add_u64 v[220:221], s[30:31], 0, v[132:133]
	s_mov_b32 m0, s54
	ds_read_b128 v[204:207], v160
	ds_read_b128 v[208:211], v160 offset:1024
	ds_read_b128 v[212:215], v160 offset:2048
	ds_read_b128 v[216:219], v160 offset:3072
	global_load_lds_dwordx4 v[220:221], off
	v_lshl_add_u64 v[222:223], s[30:31], 0, v[128:129]
	s_add_i32 m0, s54, 0x2000
	s_nop 0
	global_load_lds_dwordx4 v[222:223], off
	s_barrier
	s_waitcnt lgkmcnt(0)
	s_setprio 1
	s_waitcnt lgkmcnt(0)
	v_mfma_f32_16x16x32_bf16 v[116:119], v[204:207], v[170:173], v[116:119]
	v_mfma_f32_16x16x32_bf16 v[112:115], v[212:215], v[170:173], v[112:115]
	v_mfma_f32_16x16x32_bf16 v[100:103], v[204:207], v[178:181], v[100:103]
	v_mfma_f32_16x16x32_bf16 v[96:99], v[212:215], v[178:181], v[96:99]
	v_mfma_f32_16x16x32_bf16 v[84:87], v[204:207], v[186:189], v[84:87]
	v_mfma_f32_16x16x32_bf16 v[80:83], v[212:215], v[186:189], v[80:83]
	v_mfma_f32_16x16x32_bf16 v[68:71], v[204:207], v[196:199], v[68:71]
	v_mfma_f32_16x16x32_bf16 v[64:67], v[212:215], v[196:199], v[64:67]
	v_mfma_f32_16x16x32_bf16 v[116:119], v[208:211], v[174:177], v[116:119]
	v_mfma_f32_16x16x32_bf16 v[112:115], v[216:219], v[174:177], v[112:115]
	v_mfma_f32_16x16x32_bf16 v[100:103], v[208:211], v[182:185], v[100:103]
	v_mfma_f32_16x16x32_bf16 v[96:99], v[216:219], v[182:185], v[96:99]
	v_mfma_f32_16x16x32_bf16 v[84:87], v[208:211], v[190:193], v[84:87]
	v_mfma_f32_16x16x32_bf16 v[80:83], v[216:219], v[190:193], v[80:83]
	v_mfma_f32_16x16x32_bf16 v[68:71], v[208:211], v[200:203], v[68:71]
	v_mfma_f32_16x16x32_bf16 v[64:67], v[216:219], v[200:203], v[64:67]
	s_setprio 0
	s_mov_b32 m0, s25
	v_lshl_add_u64 v[224:225], s[20:21], 0, v[134:135]
	s_barrier
	ds_read_b128 v[170:173], v159 offset:16384
	ds_read_b128 v[174:177], v159 offset:17408
	ds_read_b128 v[178:181], v159 offset:18432
	ds_read_b128 v[182:185], v159 offset:19456
	ds_read_b128 v[186:189], v159 offset:20480
	ds_read_b128 v[190:193], v159 offset:21504
	ds_read_b128 v[196:199], v159 offset:22528
	ds_read_b128 v[200:203], v159 offset:23552
	global_load_lds_dwordx4 v[224:225], off
	v_lshl_add_u64 v[226:227], s[20:21], 0, v[130:131]
	s_mov_b32 m0, s37
	s_nop 0
	global_load_lds_dwordx4 v[226:227], off
	s_barrier
	s_waitcnt lgkmcnt(0)
	s_setprio 1
	s_waitcnt lgkmcnt(0)
	v_mfma_f32_16x16x32_bf16 v[60:63], v[148:151], v[170:173], v[60:63]
	v_mfma_f32_16x16x32_bf16 v[56:59], v[162:165], v[170:173], v[56:59]
	v_mfma_f32_16x16x32_bf16 v[44:47], v[148:151], v[178:181], v[44:47]
	v_mfma_f32_16x16x32_bf16 v[40:43], v[162:165], v[178:181], v[40:43]
	v_mfma_f32_16x16x32_bf16 v[28:31], v[148:151], v[186:189], v[28:31]
	v_mfma_f32_16x16x32_bf16 v[24:27], v[162:165], v[186:189], v[24:27]
	v_mfma_f32_16x16x32_bf16 v[12:15], v[148:151], v[196:199], v[12:15]
	v_mfma_f32_16x16x32_bf16 v[8:11], v[162:165], v[196:199], v[8:11]
	v_mfma_f32_16x16x32_bf16 v[60:63], v[152:155], v[174:177], v[60:63]
	v_mfma_f32_16x16x32_bf16 v[56:59], v[166:169], v[174:177], v[56:59]
	v_mfma_f32_16x16x32_bf16 v[44:47], v[152:155], v[182:185], v[44:47]
	v_mfma_f32_16x16x32_bf16 v[40:43], v[166:169], v[182:185], v[40:43]
	v_mfma_f32_16x16x32_bf16 v[28:31], v[152:155], v[190:193], v[28:31]
	v_mfma_f32_16x16x32_bf16 v[24:27], v[166:169], v[190:193], v[24:27]
	v_mfma_f32_16x16x32_bf16 v[12:15], v[152:155], v[200:203], v[12:15]
	v_mfma_f32_16x16x32_bf16 v[8:11], v[166:169], v[200:203], v[8:11]
	s_setprio 0
	s_barrier
	s_add_u32 s54, s30, 0x200000
	s_addc_u32 s55, s31, 0
	s_add_i32 s56, s47, s23
	v_lshl_add_u64 v[148:149], s[54:55], 0, v[132:133]
	s_mov_b32 m0, s56
	s_nop 0
	global_load_lds_dwordx4 v[148:149], off
	v_lshl_add_u64 v[148:149], s[54:55], 0, v[128:129]
	s_add_i32 m0, s56, 0x2000
	s_nop 0
	global_load_lds_dwordx4 v[148:149], off
	s_waitcnt vmcnt(6)
	s_barrier
	s_setprio 1
	v_mfma_f32_16x16x32_bf16 v[52:55], v[204:207], v[170:173], v[52:55]
	v_mfma_f32_16x16x32_bf16 v[48:51], v[212:215], v[170:173], v[48:51]
	v_mfma_f32_16x16x32_bf16 v[36:39], v[204:207], v[178:181], v[36:39]
	v_mfma_f32_16x16x32_bf16 v[32:35], v[212:215], v[178:181], v[32:35]
	v_mfma_f32_16x16x32_bf16 v[20:23], v[204:207], v[186:189], v[20:23]
	v_mfma_f32_16x16x32_bf16 v[16:19], v[212:215], v[186:189], v[16:19]
	v_mfma_f32_16x16x32_bf16 v[4:7], v[204:207], v[196:199], v[4:7]
	v_mfma_f32_16x16x32_bf16 v[0:3], v[212:215], v[196:199], v[0:3]
	v_mfma_f32_16x16x32_bf16 v[52:55], v[208:211], v[174:177], v[52:55]
	v_mfma_f32_16x16x32_bf16 v[48:51], v[216:219], v[174:177], v[48:51]
	v_mfma_f32_16x16x32_bf16 v[36:39], v[208:211], v[182:185], v[36:39]
	v_mfma_f32_16x16x32_bf16 v[32:35], v[216:219], v[182:185], v[32:35]
	v_mfma_f32_16x16x32_bf16 v[20:23], v[208:211], v[190:193], v[20:23]
	v_mfma_f32_16x16x32_bf16 v[16:19], v[216:219], v[190:193], v[16:19]
	v_mfma_f32_16x16x32_bf16 v[4:7], v[208:211], v[200:203], v[4:7]
	v_mfma_f32_16x16x32_bf16 v[0:3], v[216:219], v[200:203], v[0:3]
	s_setprio 0
	s_add_i32 s54, 0, 0x18000
	v_add_u32_e32 v161, s54, v147
	s_barrier
	ds_read_b128 v[148:151], v161
	ds_read_b128 v[152:155], v161 offset:1024
	ds_read_b128 v[162:165], v161 offset:2048
	ds_read_b128 v[166:169], v161 offset:3072
	s_add_u32 s20, s20, 0x200000
	s_addc_u32 s21, s21, 0
	s_mov_b32 m0, s38
	v_lshl_add_u64 v[204:205], s[20:21], 0, v[134:135]
	ds_read_b128 v[170:173], v159 offset:32768
	ds_read_b128 v[174:177], v159 offset:33792
	ds_read_b128 v[178:181], v159 offset:34816
	ds_read_b128 v[182:185], v159 offset:35840
	ds_read_b128 v[186:189], v159 offset:36864
	ds_read_b128 v[190:193], v159 offset:37888
	ds_read_b128 v[196:199], v159 offset:38912
	ds_read_b128 v[200:203], v159 offset:39936
	global_load_lds_dwordx4 v[204:205], off
	v_lshl_add_u64 v[204:205], s[20:21], 0, v[130:131]
	s_mov_b32 m0, s39
	s_nop 0
	global_load_lds_dwordx4 v[204:205], off
	s_waitcnt lgkmcnt(8)
	s_barrier
	s_waitcnt lgkmcnt(0)
	s_setprio 1
	s_waitcnt lgkmcnt(0)
	v_mfma_f32_16x16x32_bf16 v[124:127], v[148:151], v[170:173], v[124:127]
	v_mfma_f32_16x16x32_bf16 v[120:123], v[162:165], v[170:173], v[120:123]
	v_mfma_f32_16x16x32_bf16 v[108:111], v[148:151], v[178:181], v[108:111]
	v_mfma_f32_16x16x32_bf16 v[104:107], v[162:165], v[178:181], v[104:107]
	v_mfma_f32_16x16x32_bf16 v[92:95], v[148:151], v[186:189], v[92:95]
	v_mfma_f32_16x16x32_bf16 v[88:91], v[162:165], v[186:189], v[88:91]
	v_mfma_f32_16x16x32_bf16 v[76:79], v[148:151], v[196:199], v[76:79]
	v_mfma_f32_16x16x32_bf16 v[72:75], v[162:165], v[196:199], v[72:75]
	v_mfma_f32_16x16x32_bf16 v[124:127], v[152:155], v[174:177], v[124:127]
	v_mfma_f32_16x16x32_bf16 v[120:123], v[166:169], v[174:177], v[120:123]
	v_mfma_f32_16x16x32_bf16 v[108:111], v[152:155], v[182:185], v[108:111]
	v_mfma_f32_16x16x32_bf16 v[104:107], v[166:169], v[182:185], v[104:107]
	v_mfma_f32_16x16x32_bf16 v[92:95], v[152:155], v[190:193], v[92:95]
	v_mfma_f32_16x16x32_bf16 v[88:91], v[166:169], v[190:193], v[88:91]
	v_mfma_f32_16x16x32_bf16 v[76:79], v[152:155], v[200:203], v[76:79]
	v_mfma_f32_16x16x32_bf16 v[72:75], v[166:169], v[200:203], v[72:75]
	s_setprio 0
	s_barrier
	s_add_i32 s55, 0, 0x1c000
	s_add_i32 s20, s54, s23
	v_add_u32_e32 v161, s55, v147
	v_lshl_add_u64 v[220:221], v[220:221], 0, s[8:9]
	s_mov_b32 m0, s20
	ds_read_b128 v[204:207], v161
	ds_read_b128 v[208:211], v161 offset:1024
	ds_read_b128 v[212:215], v161 offset:2048
	ds_read_b128 v[216:219], v161 offset:3072
	global_load_lds_dwordx4 v[220:221], off
	v_lshl_add_u64 v[220:221], v[222:223], 0, s[8:9]
	s_add_i32 m0, s20, 0x2000
	s_nop 0
	global_load_lds_dwordx4 v[220:221], off
	s_barrier
	s_waitcnt lgkmcnt(0)
	s_setprio 1
	s_waitcnt lgkmcnt(0)
	v_mfma_f32_16x16x32_bf16 v[116:119], v[204:207], v[170:173], v[116:119]
	v_mfma_f32_16x16x32_bf16 v[112:115], v[212:215], v[170:173], v[112:115]
	v_mfma_f32_16x16x32_bf16 v[100:103], v[204:207], v[178:181], v[100:103]
	v_mfma_f32_16x16x32_bf16 v[96:99], v[212:215], v[178:181], v[96:99]
	v_mfma_f32_16x16x32_bf16 v[84:87], v[204:207], v[186:189], v[84:87]
	v_mfma_f32_16x16x32_bf16 v[80:83], v[212:215], v[186:189], v[80:83]
	v_mfma_f32_16x16x32_bf16 v[68:71], v[204:207], v[196:199], v[68:71]
	v_mfma_f32_16x16x32_bf16 v[64:67], v[212:215], v[196:199], v[64:67]
	v_mfma_f32_16x16x32_bf16 v[116:119], v[208:211], v[174:177], v[116:119]
	v_mfma_f32_16x16x32_bf16 v[112:115], v[216:219], v[174:177], v[112:115]
	v_mfma_f32_16x16x32_bf16 v[100:103], v[208:211], v[182:185], v[100:103]
	v_mfma_f32_16x16x32_bf16 v[96:99], v[216:219], v[182:185], v[96:99]
	v_mfma_f32_16x16x32_bf16 v[84:87], v[208:211], v[190:193], v[84:87]
	v_mfma_f32_16x16x32_bf16 v[80:83], v[216:219], v[190:193], v[80:83]
	v_mfma_f32_16x16x32_bf16 v[68:71], v[208:211], v[200:203], v[68:71]
	v_mfma_f32_16x16x32_bf16 v[64:67], v[216:219], v[200:203], v[64:67]
	s_setprio 0
	s_mov_b32 m0, s35
	v_lshl_add_u64 v[220:221], v[224:225], 0, s[8:9]
	s_barrier
	ds_read_b128 v[170:173], v159 offset:49152
	ds_read_b128 v[174:177], v159 offset:50176
	ds_read_b128 v[178:181], v159 offset:51200
	ds_read_b128 v[182:185], v159 offset:52224
	ds_read_b128 v[186:189], v159 offset:53248
	ds_read_b128 v[190:193], v159 offset:54272
	ds_read_b128 v[196:199], v159 offset:55296
	ds_read_b128 v[200:203], v159 offset:56320
	global_load_lds_dwordx4 v[220:221], off
	v_lshl_add_u64 v[220:221], v[226:227], 0, s[8:9]
	s_mov_b32 m0, s41
	s_nop 0
	global_load_lds_dwordx4 v[220:221], off
	s_barrier
	s_waitcnt lgkmcnt(0)
	s_setprio 1
	s_waitcnt lgkmcnt(0)
	v_mfma_f32_16x16x32_bf16 v[60:63], v[148:151], v[170:173], v[60:63]
	v_mfma_f32_16x16x32_bf16 v[56:59], v[162:165], v[170:173], v[56:59]
	v_mfma_f32_16x16x32_bf16 v[44:47], v[148:151], v[178:181], v[44:47]
	v_mfma_f32_16x16x32_bf16 v[40:43], v[162:165], v[178:181], v[40:43]
	v_mfma_f32_16x16x32_bf16 v[28:31], v[148:151], v[186:189], v[28:31]
	v_mfma_f32_16x16x32_bf16 v[24:27], v[162:165], v[186:189], v[24:27]
	v_mfma_f32_16x16x32_bf16 v[12:15], v[148:151], v[196:199], v[12:15]
	v_mfma_f32_16x16x32_bf16 v[8:11], v[162:165], v[196:199], v[8:11]
	v_mfma_f32_16x16x32_bf16 v[60:63], v[152:155], v[174:177], v[60:63]
	v_mfma_f32_16x16x32_bf16 v[56:59], v[166:169], v[174:177], v[56:59]
	v_mfma_f32_16x16x32_bf16 v[44:47], v[152:155], v[182:185], v[44:47]
	v_mfma_f32_16x16x32_bf16 v[40:43], v[166:169], v[182:185], v[40:43]
	v_mfma_f32_16x16x32_bf16 v[28:31], v[152:155], v[190:193], v[28:31]
	v_mfma_f32_16x16x32_bf16 v[24:27], v[166:169], v[190:193], v[24:27]
	v_mfma_f32_16x16x32_bf16 v[12:15], v[152:155], v[200:203], v[12:15]
	v_mfma_f32_16x16x32_bf16 v[8:11], v[166:169], v[200:203], v[8:11]
	s_setprio 0
	s_barrier
	s_add_u32 s20, s30, 0x200080
	s_addc_u32 s21, s31, 0
	s_add_i32 s30, s55, s23
	v_lshl_add_u64 v[148:149], s[20:21], 0, v[132:133]
	s_mov_b32 m0, s30
	s_nop 0
	global_load_lds_dwordx4 v[148:149], off
	v_lshl_add_u64 v[148:149], s[20:21], 0, v[128:129]
	s_add_i32 m0, s30, 0x2000
	s_nop 0
	global_load_lds_dwordx4 v[148:149], off
	s_waitcnt vmcnt(6)
	s_barrier
	s_setprio 1
	v_mfma_f32_16x16x32_bf16 v[52:55], v[204:207], v[170:173], v[52:55]
	v_mfma_f32_16x16x32_bf16 v[48:51], v[212:215], v[170:173], v[48:51]
	v_mfma_f32_16x16x32_bf16 v[36:39], v[204:207], v[178:181], v[36:39]
	v_mfma_f32_16x16x32_bf16 v[32:35], v[212:215], v[178:181], v[32:35]
	v_mfma_f32_16x16x32_bf16 v[20:23], v[204:207], v[186:189], v[20:23]
	v_mfma_f32_16x16x32_bf16 v[16:19], v[212:215], v[186:189], v[16:19]
	v_mfma_f32_16x16x32_bf16 v[4:7], v[204:207], v[196:199], v[4:7]
	v_mfma_f32_16x16x32_bf16 v[0:3], v[212:215], v[196:199], v[0:3]
	v_mfma_f32_16x16x32_bf16 v[52:55], v[208:211], v[174:177], v[52:55]
	v_mfma_f32_16x16x32_bf16 v[48:51], v[216:219], v[174:177], v[48:51]
	v_mfma_f32_16x16x32_bf16 v[36:39], v[208:211], v[182:185], v[36:39]
	v_mfma_f32_16x16x32_bf16 v[32:35], v[216:219], v[182:185], v[32:35]
	v_mfma_f32_16x16x32_bf16 v[20:23], v[208:211], v[190:193], v[20:23]
	v_mfma_f32_16x16x32_bf16 v[16:19], v[216:219], v[190:193], v[16:19]
	v_mfma_f32_16x16x32_bf16 v[4:7], v[208:211], v[200:203], v[4:7]
	v_mfma_f32_16x16x32_bf16 v[0:3], v[216:219], v[200:203], v[0:3]
	s_setprio 0
	s_add_i32 s53, s53, 2
	s_add_u32 s26, s26, 0x100
	s_addc_u32 s27, s27, 0
	s_add_u32 s51, s51, 0x100
	s_addc_u32 s52, s52, 0
	s_cmpk_gt_u32 s53, 0x7d
	s_cbranch_scc0 .Lepi_nl_mlpout1
	s_cmp_lg_u32 s34, 64
	s_cbranch_scc1 .Lepi_nl_mlpout1
	s_lshl_b32 s11, s24, 8
	s_add_i32 s11, s11, s34
	v_or_b32_e32 v154, s11, v145
	s_add_i32 s15, s11, 0xffffe000
	v_lshl_or_b32 v150, s33, 8, v157
	s_lshr_b32 s15, s15, 12
	v_lshlrev_b32_e32 v148, 12, v154
	s_add_i32 s15, s15, 1
	s_cmp_gt_i32 s11, s48
	s_cselect_b32 s15, s15, 0
	s_mul_i32 s15, s15, s46
	v_lshl_add_u32 v148, v150, 1, v148
	s_add_u32 s20, s6, s15
	s_addc_u32 s21, s7, 0
	v_lshlrev_b32_e32 v149, 2, v150
	s_nop 0
	global_load_dwordx4 v[196:199], v149, s[20:21]
	global_load_dwordx4 v[200:203], v149, s[20:21] offset:16
	global_load_dwordx4 v[204:207], v149, s[20:21] offset:512
	global_load_dwordx4 v[208:211], v149, s[20:21] offset:528
	global_load_dwordx4 v[212:215], v148, s[74:75]
	global_load_dwordx4 v[216:219], v148, s[74:75] offset:256
	v_add_u32_e32 v151, 0x10000, v148
	global_load_dwordx4 v[220:223], v151, s[74:75]
	global_load_dwordx4 v[224:227], v151, s[74:75] offset:256
	v_add_u32_e32 v151, 0x20000, v148
	global_load_dwordx4 v[164:167], v151, s[74:75]
	global_load_dwordx4 v[168:171], v151, s[74:75] offset:256
	v_add_u32_e32 v151, 0x30000, v148
	global_load_dwordx4 v[172:175], v151, s[74:75]
	global_load_dwordx4 v[176:179], v151, s[74:75] offset:256
	s_waitcnt vmcnt(0)
	v_lshlrev_b32_e32 v180, 16, v212
	v_and_b32_e32 v181, 0xffff0000, v212
	v_lshlrev_b32_e32 v182, 16, v213
	v_and_b32_e32 v183, 0xffff0000, v213
	v_lshlrev_b32_e32 v184, 16, v214
	v_and_b32_e32 v185, 0xffff0000, v214
	v_lshlrev_b32_e32 v186, 16, v215
	v_and_b32_e32 v187, 0xffff0000, v215
	v_pk_fma_f32 v[124:125], v[124:125], v[196:197], v[180:181]
	v_pk_fma_f32 v[126:127], v[126:127], v[198:199], v[182:183]
	v_pk_fma_f32 v[120:121], v[120:121], v[200:201], v[184:185]
	v_pk_fma_f32 v[122:123], v[122:123], v[202:203], v[186:187]
	v_cvt_pk_bf16_f32 v123, v122, v123
	v_cvt_pk_bf16_f32 v122, v120, v121
	v_cvt_pk_bf16_f32 v121, v126, v127
	v_cvt_pk_bf16_f32 v120, v124, v125
	global_store_dwordx4 v148, v[120:123], s[42:43]
	v_lshlrev_b32_e32 v180, 16, v216
	v_and_b32_e32 v181, 0xffff0000, v216
	v_lshlrev_b32_e32 v182, 16, v217
	v_and_b32_e32 v183, 0xffff0000, v217
	v_lshlrev_b32_e32 v184, 16, v218
	v_and_b32_e32 v185, 0xffff0000, v218
	v_lshlrev_b32_e32 v186, 16, v219
	v_and_b32_e32 v187, 0xffff0000, v219
	v_pk_fma_f32 v[116:117], v[116:117], v[204:205], v[180:181]
	v_pk_fma_f32 v[118:119], v[118:119], v[206:207], v[182:183]
	v_pk_fma_f32 v[112:113], v[112:113], v[208:209], v[184:185]
	v_pk_fma_f32 v[114:115], v[114:115], v[210:211], v[186:187]
	v_cvt_pk_bf16_f32 v115, v114, v115
	v_cvt_pk_bf16_f32 v114, v112, v113
	v_cvt_pk_bf16_f32 v113, v118, v119
	v_cvt_pk_bf16_f32 v112, v116, v117
	global_store_dwordx4 v148, v[112:115], s[42:43] offset:256
	v_lshlrev_b32_e32 v180, 16, v220
	v_and_b32_e32 v181, 0xffff0000, v220
	v_lshlrev_b32_e32 v182, 16, v221
	v_and_b32_e32 v183, 0xffff0000, v221
	v_lshlrev_b32_e32 v184, 16, v222
	v_and_b32_e32 v185, 0xffff0000, v222
	v_lshlrev_b32_e32 v186, 16, v223
	v_and_b32_e32 v187, 0xffff0000, v223
	v_pk_fma_f32 v[108:109], v[108:109], v[196:197], v[180:181]
	v_pk_fma_f32 v[110:111], v[110:111], v[198:199], v[182:183]
	v_pk_fma_f32 v[104:105], v[104:105], v[200:201], v[184:185]
	v_pk_fma_f32 v[106:107], v[106:107], v[202:203], v[186:187]
	v_cvt_pk_bf16_f32 v107, v106, v107
	v_cvt_pk_bf16_f32 v106, v104, v105
	v_cvt_pk_bf16_f32 v105, v110, v111
	v_cvt_pk_bf16_f32 v104, v108, v109
	v_add_u32_e32 v151, 0x10000, v148
	global_store_dwordx4 v151, v[104:107], s[42:43]
	v_lshlrev_b32_e32 v180, 16, v224
	v_and_b32_e32 v181, 0xffff0000, v224
	v_lshlrev_b32_e32 v182, 16, v225
	v_and_b32_e32 v183, 0xffff0000, v225
	v_lshlrev_b32_e32 v184, 16, v226
	v_and_b32_e32 v185, 0xffff0000, v226
	v_lshlrev_b32_e32 v186, 16, v227
	v_and_b32_e32 v187, 0xffff0000, v227
	v_pk_fma_f32 v[100:101], v[100:101], v[204:205], v[180:181]
	v_pk_fma_f32 v[102:103], v[102:103], v[206:207], v[182:183]
	v_pk_fma_f32 v[96:97], v[96:97], v[208:209], v[184:185]
	v_pk_fma_f32 v[98:99], v[98:99], v[210:211], v[186:187]
	v_cvt_pk_bf16_f32 v99, v98, v99
	v_cvt_pk_bf16_f32 v98, v96, v97
	v_cvt_pk_bf16_f32 v97, v102, v103
	v_cvt_pk_bf16_f32 v96, v100, v101
	v_add_u32_e32 v151, 0x10000, v148
	global_store_dwordx4 v151, v[96:99], s[42:43] offset:256
	v_add_u32_e32 v151, 0x80000, v148
	global_load_dwordx4 v[212:215], v151, s[74:75]
	global_load_dwordx4 v[216:219], v151, s[74:75] offset:256
	v_add_u32_e32 v151, 0x90000, v148
	global_load_dwordx4 v[220:223], v151, s[74:75]
	global_load_dwordx4 v[224:227], v151, s[74:75] offset:256
	v_lshlrev_b32_e32 v180, 16, v164
	v_and_b32_e32 v181, 0xffff0000, v164
	v_lshlrev_b32_e32 v182, 16, v165
	v_and_b32_e32 v183, 0xffff0000, v165
	v_lshlrev_b32_e32 v184, 16, v166
	v_and_b32_e32 v185, 0xffff0000, v166
	v_lshlrev_b32_e32 v186, 16, v167
	v_and_b32_e32 v187, 0xffff0000, v167
	v_pk_fma_f32 v[92:93], v[92:93], v[196:197], v[180:181]
	v_pk_fma_f32 v[94:95], v[94:95], v[198:199], v[182:183]
	v_pk_fma_f32 v[88:89], v[88:89], v[200:201], v[184:185]
	v_pk_fma_f32 v[90:91], v[90:91], v[202:203], v[186:187]
	v_cvt_pk_bf16_f32 v91, v90, v91
	v_cvt_pk_bf16_f32 v90, v88, v89
	v_cvt_pk_bf16_f32 v89, v94, v95
	v_cvt_pk_bf16_f32 v88, v92, v93
	v_add_u32_e32 v151, 0x20000, v148
	global_store_dwordx4 v151, v[88:91], s[42:43]
	v_lshlrev_b32_e32 v180, 16, v168
	v_and_b32_e32 v181, 0xffff0000, v168
	v_lshlrev_b32_e32 v182, 16, v169
	v_and_b32_e32 v183, 0xffff0000, v169
	v_lshlrev_b32_e32 v184, 16, v170
	v_and_b32_e32 v185, 0xffff0000, v170
	v_lshlrev_b32_e32 v186, 16, v171
	v_and_b32_e32 v187, 0xffff0000, v171
	v_pk_fma_f32 v[84:85], v[84:85], v[204:205], v[180:181]
	v_pk_fma_f32 v[86:87], v[86:87], v[206:207], v[182:183]
	v_pk_fma_f32 v[80:81], v[80:81], v[208:209], v[184:185]
	v_pk_fma_f32 v[82:83], v[82:83], v[210:211], v[186:187]
	v_cvt_pk_bf16_f32 v83, v82, v83
	v_cvt_pk_bf16_f32 v82, v80, v81
	v_cvt_pk_bf16_f32 v81, v86, v87
	v_cvt_pk_bf16_f32 v80, v84, v85
	v_add_u32_e32 v151, 0x20000, v148
	global_store_dwordx4 v151, v[80:83], s[42:43] offset:256
	v_lshlrev_b32_e32 v180, 16, v172
	v_and_b32_e32 v181, 0xffff0000, v172
	v_lshlrev_b32_e32 v182, 16, v173
	v_and_b32_e32 v183, 0xffff0000, v173
	v_lshlrev_b32_e32 v184, 16, v174
	v_and_b32_e32 v185, 0xffff0000, v174
	v_lshlrev_b32_e32 v186, 16, v175
	v_and_b32_e32 v187, 0xffff0000, v175
	v_pk_fma_f32 v[76:77], v[76:77], v[196:197], v[180:181]
	v_pk_fma_f32 v[78:79], v[78:79], v[198:199], v[182:183]
	v_pk_fma_f32 v[72:73], v[72:73], v[200:201], v[184:185]
	v_pk_fma_f32 v[74:75], v[74:75], v[202:203], v[186:187]
	v_cvt_pk_bf16_f32 v75, v74, v75
	v_cvt_pk_bf16_f32 v74, v72, v73
	v_cvt_pk_bf16_f32 v73, v78, v79
	v_cvt_pk_bf16_f32 v72, v76, v77
	v_add_u32_e32 v151, 0x30000, v148
	global_store_dwordx4 v151, v[72:75], s[42:43]
	v_lshlrev_b32_e32 v180, 16, v176
	v_and_b32_e32 v181, 0xffff0000, v176
	v_lshlrev_b32_e32 v182, 16, v177
	v_and_b32_e32 v183, 0xffff0000, v177
	v_lshlrev_b32_e32 v184, 16, v178
	v_and_b32_e32 v185, 0xffff0000, v178
	v_lshlrev_b32_e32 v186, 16, v179
	v_and_b32_e32 v187, 0xffff0000, v179
	v_pk_fma_f32 v[68:69], v[68:69], v[204:205], v[180:181]
	v_pk_fma_f32 v[70:71], v[70:71], v[206:207], v[182:183]
	v_pk_fma_f32 v[64:65], v[64:65], v[208:209], v[184:185]
	v_pk_fma_f32 v[66:67], v[66:67], v[210:211], v[186:187]
	v_cvt_pk_bf16_f32 v67, v66, v67
	v_cvt_pk_bf16_f32 v66, v64, v65
	v_cvt_pk_bf16_f32 v65, v70, v71
	v_cvt_pk_bf16_f32 v64, v68, v69
	v_add_u32_e32 v151, 0x30000, v148
	global_store_dwordx4 v151, v[64:67], s[42:43] offset:256
	v_add_u32_e32 v151, 0xa0000, v148
	global_load_dwordx4 v[164:167], v151, s[74:75]
	global_load_dwordx4 v[168:171], v151, s[74:75] offset:256
	v_add_u32_e32 v151, 0xb0000, v148
	global_load_dwordx4 v[172:175], v151, s[74:75]
	global_load_dwordx4 v[176:179], v151, s[74:75] offset:256
	s_waitcnt vmcnt(0)
	v_lshlrev_b32_e32 v180, 16, v212
	v_and_b32_e32 v181, 0xffff0000, v212
	v_lshlrev_b32_e32 v182, 16, v213
	v_and_b32_e32 v183, 0xffff0000, v213
	v_lshlrev_b32_e32 v184, 16, v214
	v_and_b32_e32 v185, 0xffff0000, v214
	v_lshlrev_b32_e32 v186, 16, v215
	v_and_b32_e32 v187, 0xffff0000, v215
	v_pk_fma_f32 v[60:61], v[60:61], v[196:197], v[180:181]
	v_pk_fma_f32 v[62:63], v[62:63], v[198:199], v[182:183]
	v_pk_fma_f32 v[56:57], v[56:57], v[200:201], v[184:185]
	v_pk_fma_f32 v[58:59], v[58:59], v[202:203], v[186:187]
	v_cvt_pk_bf16_f32 v59, v58, v59
	v_cvt_pk_bf16_f32 v58, v56, v57
	v_cvt_pk_bf16_f32 v57, v62, v63
	v_cvt_pk_bf16_f32 v56, v60, v61
	v_add_u32_e32 v151, 0x80000, v148
	global_store_dwordx4 v151, v[56:59], s[42:43]
	v_lshlrev_b32_e32 v180, 16, v216
	v_and_b32_e32 v181, 0xffff0000, v216
	v_lshlrev_b32_e32 v182, 16, v217
	v_and_b32_e32 v183, 0xffff0000, v217
	v_lshlrev_b32_e32 v184, 16, v218
	v_and_b32_e32 v185, 0xffff0000, v218
	v_lshlrev_b32_e32 v186, 16, v219
	v_and_b32_e32 v187, 0xffff0000, v219
	v_pk_fma_f32 v[52:53], v[52:53], v[204:205], v[180:181]
	v_pk_fma_f32 v[54:55], v[54:55], v[206:207], v[182:183]
	v_pk_fma_f32 v[48:49], v[48:49], v[208:209], v[184:185]
	v_pk_fma_f32 v[50:51], v[50:51], v[210:211], v[186:187]
	v_cvt_pk_bf16_f32 v51, v50, v51
	v_cvt_pk_bf16_f32 v50, v48, v49
	v_cvt_pk_bf16_f32 v49, v54, v55
	v_cvt_pk_bf16_f32 v48, v52, v53
	v_add_u32_e32 v151, 0x80000, v148
	global_store_dwordx4 v151, v[48:51], s[42:43] offset:256
	v_lshlrev_b32_e32 v180, 16, v220
	v_and_b32_e32 v181, 0xffff0000, v220
	v_lshlrev_b32_e32 v182, 16, v221
	v_and_b32_e32 v183, 0xffff0000, v221
	v_lshlrev_b32_e32 v184, 16, v222
	v_and_b32_e32 v185, 0xffff0000, v222
	v_lshlrev_b32_e32 v186, 16, v223
	v_and_b32_e32 v187, 0xffff0000, v223
	v_pk_fma_f32 v[44:45], v[44:45], v[196:197], v[180:181]
	v_pk_fma_f32 v[46:47], v[46:47], v[198:199], v[182:183]
	v_pk_fma_f32 v[40:41], v[40:41], v[200:201], v[184:185]
	v_pk_fma_f32 v[42:43], v[42:43], v[202:203], v[186:187]
	v_cvt_pk_bf16_f32 v43, v42, v43
	v_cvt_pk_bf16_f32 v42, v40, v41
	v_cvt_pk_bf16_f32 v41, v46, v47
	v_cvt_pk_bf16_f32 v40, v44, v45
	v_add_u32_e32 v151, 0x90000, v148
	global_store_dwordx4 v151, v[40:43], s[42:43]
	v_lshlrev_b32_e32 v180, 16, v224
	v_and_b32_e32 v181, 0xffff0000, v224
	v_lshlrev_b32_e32 v182, 16, v225
	v_and_b32_e32 v183, 0xffff0000, v225
	v_lshlrev_b32_e32 v184, 16, v226
	v_and_b32_e32 v185, 0xffff0000, v226
	v_lshlrev_b32_e32 v186, 16, v227
	v_and_b32_e32 v187, 0xffff0000, v227
	v_pk_fma_f32 v[36:37], v[36:37], v[204:205], v[180:181]
	v_pk_fma_f32 v[38:39], v[38:39], v[206:207], v[182:183]
	v_pk_fma_f32 v[32:33], v[32:33], v[208:209], v[184:185]
	v_pk_fma_f32 v[34:35], v[34:35], v[210:211], v[186:187]
	v_cvt_pk_bf16_f32 v35, v34, v35
	v_cvt_pk_bf16_f32 v34, v32, v33
	v_cvt_pk_bf16_f32 v33, v38, v39
	v_cvt_pk_bf16_f32 v32, v36, v37
	v_add_u32_e32 v151, 0x90000, v148
	global_store_dwordx4 v151, v[32:35], s[42:43] offset:256
	v_lshlrev_b32_e32 v180, 16, v164
	v_and_b32_e32 v181, 0xffff0000, v164
	v_lshlrev_b32_e32 v182, 16, v165
	v_and_b32_e32 v183, 0xffff0000, v165
	v_lshlrev_b32_e32 v184, 16, v166
	v_and_b32_e32 v185, 0xffff0000, v166
	v_lshlrev_b32_e32 v186, 16, v167
	v_and_b32_e32 v187, 0xffff0000, v167
	v_pk_fma_f32 v[28:29], v[28:29], v[196:197], v[180:181]
	v_pk_fma_f32 v[30:31], v[30:31], v[198:199], v[182:183]
	v_pk_fma_f32 v[24:25], v[24:25], v[200:201], v[184:185]
	v_pk_fma_f32 v[26:27], v[26:27], v[202:203], v[186:187]
	v_cvt_pk_bf16_f32 v27, v26, v27
	v_cvt_pk_bf16_f32 v26, v24, v25
	v_cvt_pk_bf16_f32 v25, v30, v31
	v_cvt_pk_bf16_f32 v24, v28, v29
	v_add_u32_e32 v151, 0xa0000, v148
	global_store_dwordx4 v151, v[24:27], s[42:43]
	v_lshlrev_b32_e32 v180, 16, v168
	v_and_b32_e32 v181, 0xffff0000, v168
	v_lshlrev_b32_e32 v182, 16, v169
	v_and_b32_e32 v183, 0xffff0000, v169
	v_lshlrev_b32_e32 v184, 16, v170
	v_and_b32_e32 v185, 0xffff0000, v170
	v_lshlrev_b32_e32 v186, 16, v171
	v_and_b32_e32 v187, 0xffff0000, v171
	v_pk_fma_f32 v[20:21], v[20:21], v[204:205], v[180:181]
	v_pk_fma_f32 v[22:23], v[22:23], v[206:207], v[182:183]
	v_pk_fma_f32 v[16:17], v[16:17], v[208:209], v[184:185]
	v_pk_fma_f32 v[18:19], v[18:19], v[210:211], v[186:187]
	v_cvt_pk_bf16_f32 v19, v18, v19
	v_cvt_pk_bf16_f32 v18, v16, v17
	v_cvt_pk_bf16_f32 v17, v22, v23
	v_cvt_pk_bf16_f32 v16, v20, v21
	v_add_u32_e32 v151, 0xa0000, v148
	global_store_dwordx4 v151, v[16:19], s[42:43] offset:256
	v_lshlrev_b32_e32 v180, 16, v172
	v_and_b32_e32 v181, 0xffff0000, v172
	v_lshlrev_b32_e32 v182, 16, v173
	v_and_b32_e32 v183, 0xffff0000, v173
	v_lshlrev_b32_e32 v184, 16, v174
	v_and_b32_e32 v185, 0xffff0000, v174
	v_lshlrev_b32_e32 v186, 16, v175
	v_and_b32_e32 v187, 0xffff0000, v175
	v_pk_fma_f32 v[12:13], v[12:13], v[196:197], v[180:181]
	v_pk_fma_f32 v[14:15], v[14:15], v[198:199], v[182:183]
	v_pk_fma_f32 v[8:9], v[8:9], v[200:201], v[184:185]
	v_pk_fma_f32 v[10:11], v[10:11], v[202:203], v[186:187]
	v_cvt_pk_bf16_f32 v11, v10, v11
	v_cvt_pk_bf16_f32 v10, v8, v9
	v_cvt_pk_bf16_f32 v9, v14, v15
	v_cvt_pk_bf16_f32 v8, v12, v13
	v_add_u32_e32 v151, 0xb0000, v148
	global_store_dwordx4 v151, v[8:11], s[42:43]
	v_lshlrev_b32_e32 v180, 16, v176
	v_and_b32_e32 v181, 0xffff0000, v176
	v_lshlrev_b32_e32 v182, 16, v177
	v_and_b32_e32 v183, 0xffff0000, v177
	v_lshlrev_b32_e32 v184, 16, v178
	v_and_b32_e32 v185, 0xffff0000, v178
	v_lshlrev_b32_e32 v186, 16, v179
	v_and_b32_e32 v187, 0xffff0000, v179
	v_pk_fma_f32 v[4:5], v[4:5], v[204:205], v[180:181]
	v_pk_fma_f32 v[6:7], v[6:7], v[206:207], v[182:183]
	v_pk_fma_f32 v[0:1], v[0:1], v[208:209], v[184:185]
	v_pk_fma_f32 v[2:3], v[2:3], v[210:211], v[186:187]
	v_cvt_pk_bf16_f32 v3, v2, v3
	v_cvt_pk_bf16_f32 v2, v0, v1
	v_cvt_pk_bf16_f32 v1, v6, v7
	v_cvt_pk_bf16_f32 v0, v4, v5
	v_add_u32_e32 v151, 0xb0000, v148
	global_store_dwordx4 v151, v[0:3], s[42:43] offset:256
.Lepi_nl_mlpout1:
	s_cmpk_gt_u32 s53, 0x7d
	s_barrier
	s_cbranch_scc0 .LBB0_1433
	s_cmp_lg_u32 s34, 0
	s_cbranch_scc1 .Lepi_g0done_mlpout1
	s_lshl_b32 s11, s24, 8
	s_add_i32 s11, s11, s34
	v_or_b32_e32 v154, s11, v145
	s_add_i32 s15, s11, 0xffffe000
	v_lshl_or_b32 v150, s33, 8, v157
	s_lshr_b32 s15, s15, 12
	v_lshlrev_b32_e32 v148, 12, v154
	s_add_i32 s15, s15, 1
	s_cmp_gt_i32 s11, s48
	s_cselect_b32 s15, s15, 0
	s_mul_i32 s15, s15, s46
	v_lshl_add_u32 v148, v150, 1, v148
	s_add_u32 s20, s6, s15
	s_addc_u32 s21, s7, 0
	v_lshlrev_b32_e32 v149, 2, v150
	s_nop 0
	global_load_dwordx4 v[196:199], v149, s[20:21]
	global_load_dwordx4 v[200:203], v149, s[20:21] offset:16
	global_load_dwordx4 v[204:207], v149, s[20:21] offset:512
	global_load_dwordx4 v[208:211], v149, s[20:21] offset:528
	global_load_dwordx4 v[212:215], v148, s[74:75]
	global_load_dwordx4 v[216:219], v148, s[74:75] offset:256
	v_add_u32_e32 v151, 0x10000, v148
	global_load_dwordx4 v[220:223], v151, s[74:75]
	global_load_dwordx4 v[224:227], v151, s[74:75] offset:256
	v_add_u32_e32 v151, 0x20000, v148
	global_load_dwordx4 v[164:167], v151, s[74:75]
	global_load_dwordx4 v[168:171], v151, s[74:75] offset:256
	v_add_u32_e32 v151, 0x30000, v148
	global_load_dwordx4 v[172:175], v151, s[74:75]
	global_load_dwordx4 v[176:179], v151, s[74:75] offset:256
	s_waitcnt vmcnt(0)
	v_lshlrev_b32_e32 v180, 16, v212
	v_and_b32_e32 v181, 0xffff0000, v212
	v_lshlrev_b32_e32 v182, 16, v213
	v_and_b32_e32 v183, 0xffff0000, v213
	v_lshlrev_b32_e32 v184, 16, v214
	v_and_b32_e32 v185, 0xffff0000, v214
	v_lshlrev_b32_e32 v186, 16, v215
	v_and_b32_e32 v187, 0xffff0000, v215
	v_pk_fma_f32 v[124:125], v[124:125], v[196:197], v[180:181]
	v_pk_fma_f32 v[126:127], v[126:127], v[198:199], v[182:183]
	v_pk_fma_f32 v[120:121], v[120:121], v[200:201], v[184:185]
	v_pk_fma_f32 v[122:123], v[122:123], v[202:203], v[186:187]
	v_cvt_pk_bf16_f32 v123, v122, v123
	v_cvt_pk_bf16_f32 v122, v120, v121
	v_cvt_pk_bf16_f32 v121, v126, v127
	v_cvt_pk_bf16_f32 v120, v124, v125
	global_store_dwordx4 v148, v[120:123], s[42:43]
	v_lshlrev_b32_e32 v180, 16, v216
	v_and_b32_e32 v181, 0xffff0000, v216
	v_lshlrev_b32_e32 v182, 16, v217
	v_and_b32_e32 v183, 0xffff0000, v217
	v_lshlrev_b32_e32 v184, 16, v218
	v_and_b32_e32 v185, 0xffff0000, v218
	v_lshlrev_b32_e32 v186, 16, v219
	v_and_b32_e32 v187, 0xffff0000, v219
	v_pk_fma_f32 v[116:117], v[116:117], v[204:205], v[180:181]
	v_pk_fma_f32 v[118:119], v[118:119], v[206:207], v[182:183]
	v_pk_fma_f32 v[112:113], v[112:113], v[208:209], v[184:185]
	v_pk_fma_f32 v[114:115], v[114:115], v[210:211], v[186:187]
	v_cvt_pk_bf16_f32 v115, v114, v115
	v_cvt_pk_bf16_f32 v114, v112, v113
	v_cvt_pk_bf16_f32 v113, v118, v119
	v_cvt_pk_bf16_f32 v112, v116, v117
	global_store_dwordx4 v148, v[112:115], s[42:43] offset:256
	v_lshlrev_b32_e32 v180, 16, v220
	v_and_b32_e32 v181, 0xffff0000, v220
	v_lshlrev_b32_e32 v182, 16, v221
	v_and_b32_e32 v183, 0xffff0000, v221
	v_lshlrev_b32_e32 v184, 16, v222
	v_and_b32_e32 v185, 0xffff0000, v222
	v_lshlrev_b32_e32 v186, 16, v223
	v_and_b32_e32 v187, 0xffff0000, v223
	v_pk_fma_f32 v[108:109], v[108:109], v[196:197], v[180:181]
	v_pk_fma_f32 v[110:111], v[110:111], v[198:199], v[182:183]
	v_pk_fma_f32 v[104:105], v[104:105], v[200:201], v[184:185]
	v_pk_fma_f32 v[106:107], v[106:107], v[202:203], v[186:187]
	v_cvt_pk_bf16_f32 v107, v106, v107
	v_cvt_pk_bf16_f32 v106, v104, v105
	v_cvt_pk_bf16_f32 v105, v110, v111
	v_cvt_pk_bf16_f32 v104, v108, v109
	v_add_u32_e32 v151, 0x10000, v148
	global_store_dwordx4 v151, v[104:107], s[42:43]
	v_lshlrev_b32_e32 v180, 16, v224
	v_and_b32_e32 v181, 0xffff0000, v224
	v_lshlrev_b32_e32 v182, 16, v225
	v_and_b32_e32 v183, 0xffff0000, v225
	v_lshlrev_b32_e32 v184, 16, v226
	v_and_b32_e32 v185, 0xffff0000, v226
	v_lshlrev_b32_e32 v186, 16, v227
	v_and_b32_e32 v187, 0xffff0000, v227
	v_pk_fma_f32 v[100:101], v[100:101], v[204:205], v[180:181]
	v_pk_fma_f32 v[102:103], v[102:103], v[206:207], v[182:183]
	v_pk_fma_f32 v[96:97], v[96:97], v[208:209], v[184:185]
	v_pk_fma_f32 v[98:99], v[98:99], v[210:211], v[186:187]
	v_cvt_pk_bf16_f32 v99, v98, v99
	v_cvt_pk_bf16_f32 v98, v96, v97
	v_cvt_pk_bf16_f32 v97, v102, v103
	v_cvt_pk_bf16_f32 v96, v100, v101
	v_add_u32_e32 v151, 0x10000, v148
	global_store_dwordx4 v151, v[96:99], s[42:43] offset:256
	v_add_u32_e32 v151, 0x80000, v148
	global_load_dwordx4 v[212:215], v151, s[74:75]
	global_load_dwordx4 v[216:219], v151, s[74:75] offset:256
	v_add_u32_e32 v151, 0x90000, v148
	global_load_dwordx4 v[220:223], v151, s[74:75]
	global_load_dwordx4 v[224:227], v151, s[74:75] offset:256
	v_lshlrev_b32_e32 v180, 16, v164
	v_and_b32_e32 v181, 0xffff0000, v164
	v_lshlrev_b32_e32 v182, 16, v165
	v_and_b32_e32 v183, 0xffff0000, v165
	v_lshlrev_b32_e32 v184, 16, v166
	v_and_b32_e32 v185, 0xffff0000, v166
	v_lshlrev_b32_e32 v186, 16, v167
	v_and_b32_e32 v187, 0xffff0000, v167
	v_pk_fma_f32 v[92:93], v[92:93], v[196:197], v[180:181]
	v_pk_fma_f32 v[94:95], v[94:95], v[198:199], v[182:183]
	v_pk_fma_f32 v[88:89], v[88:89], v[200:201], v[184:185]
	v_pk_fma_f32 v[90:91], v[90:91], v[202:203], v[186:187]
	v_cvt_pk_bf16_f32 v91, v90, v91
	v_cvt_pk_bf16_f32 v90, v88, v89
	v_cvt_pk_bf16_f32 v89, v94, v95
	v_cvt_pk_bf16_f32 v88, v92, v93
	v_add_u32_e32 v151, 0x20000, v148
	global_store_dwordx4 v151, v[88:91], s[42:43]
	v_lshlrev_b32_e32 v180, 16, v168
	v_and_b32_e32 v181, 0xffff0000, v168
	v_lshlrev_b32_e32 v182, 16, v169
	v_and_b32_e32 v183, 0xffff0000, v169
	v_lshlrev_b32_e32 v184, 16, v170
	v_and_b32_e32 v185, 0xffff0000, v170
	v_lshlrev_b32_e32 v186, 16, v171
	v_and_b32_e32 v187, 0xffff0000, v171
	v_pk_fma_f32 v[84:85], v[84:85], v[204:205], v[180:181]
	v_pk_fma_f32 v[86:87], v[86:87], v[206:207], v[182:183]
	v_pk_fma_f32 v[80:81], v[80:81], v[208:209], v[184:185]
	v_pk_fma_f32 v[82:83], v[82:83], v[210:211], v[186:187]
	v_cvt_pk_bf16_f32 v83, v82, v83
	v_cvt_pk_bf16_f32 v82, v80, v81
	v_cvt_pk_bf16_f32 v81, v86, v87
	v_cvt_pk_bf16_f32 v80, v84, v85
	v_add_u32_e32 v151, 0x20000, v148
	global_store_dwordx4 v151, v[80:83], s[42:43] offset:256
	v_lshlrev_b32_e32 v180, 16, v172
	v_and_b32_e32 v181, 0xffff0000, v172
	v_lshlrev_b32_e32 v182, 16, v173
	v_and_b32_e32 v183, 0xffff0000, v173
	v_lshlrev_b32_e32 v184, 16, v174
	v_and_b32_e32 v185, 0xffff0000, v174
	v_lshlrev_b32_e32 v186, 16, v175
	v_and_b32_e32 v187, 0xffff0000, v175
	v_pk_fma_f32 v[76:77], v[76:77], v[196:197], v[180:181]
	v_pk_fma_f32 v[78:79], v[78:79], v[198:199], v[182:183]
	v_pk_fma_f32 v[72:73], v[72:73], v[200:201], v[184:185]
	v_pk_fma_f32 v[74:75], v[74:75], v[202:203], v[186:187]
	v_cvt_pk_bf16_f32 v75, v74, v75
	v_cvt_pk_bf16_f32 v74, v72, v73
	v_cvt_pk_bf16_f32 v73, v78, v79
	v_cvt_pk_bf16_f32 v72, v76, v77
	v_add_u32_e32 v151, 0x30000, v148
	global_store_dwordx4 v151, v[72:75], s[42:43]
	v_lshlrev_b32_e32 v180, 16, v176
	v_and_b32_e32 v181, 0xffff0000, v176
	v_lshlrev_b32_e32 v182, 16, v177
	v_and_b32_e32 v183, 0xffff0000, v177
	v_lshlrev_b32_e32 v184, 16, v178
	v_and_b32_e32 v185, 0xffff0000, v178
	v_lshlrev_b32_e32 v186, 16, v179
	v_and_b32_e32 v187, 0xffff0000, v179
	v_pk_fma_f32 v[68:69], v[68:69], v[204:205], v[180:181]
	v_pk_fma_f32 v[70:71], v[70:71], v[206:207], v[182:183]
	v_pk_fma_f32 v[64:65], v[64:65], v[208:209], v[184:185]
	v_pk_fma_f32 v[66:67], v[66:67], v[210:211], v[186:187]
	v_cvt_pk_bf16_f32 v67, v66, v67
	v_cvt_pk_bf16_f32 v66, v64, v65
	v_cvt_pk_bf16_f32 v65, v70, v71
	v_cvt_pk_bf16_f32 v64, v68, v69
	v_add_u32_e32 v151, 0x30000, v148
	global_store_dwordx4 v151, v[64:67], s[42:43] offset:256
	v_add_u32_e32 v151, 0xa0000, v148
	global_load_dwordx4 v[164:167], v151, s[74:75]
	global_load_dwordx4 v[168:171], v151, s[74:75] offset:256
	v_add_u32_e32 v151, 0xb0000, v148
	global_load_dwordx4 v[172:175], v151, s[74:75]
	global_load_dwordx4 v[176:179], v151, s[74:75] offset:256
	s_waitcnt vmcnt(0)
	v_lshlrev_b32_e32 v180, 16, v212
	v_and_b32_e32 v181, 0xffff0000, v212
	v_lshlrev_b32_e32 v182, 16, v213
	v_and_b32_e32 v183, 0xffff0000, v213
	v_lshlrev_b32_e32 v184, 16, v214
	v_and_b32_e32 v185, 0xffff0000, v214
	v_lshlrev_b32_e32 v186, 16, v215
	v_and_b32_e32 v187, 0xffff0000, v215
	v_pk_fma_f32 v[60:61], v[60:61], v[196:197], v[180:181]
	v_pk_fma_f32 v[62:63], v[62:63], v[198:199], v[182:183]
	v_pk_fma_f32 v[56:57], v[56:57], v[200:201], v[184:185]
	v_pk_fma_f32 v[58:59], v[58:59], v[202:203], v[186:187]
	v_cvt_pk_bf16_f32 v59, v58, v59
	v_cvt_pk_bf16_f32 v58, v56, v57
	v_cvt_pk_bf16_f32 v57, v62, v63
	v_cvt_pk_bf16_f32 v56, v60, v61
	v_add_u32_e32 v151, 0x80000, v148
	global_store_dwordx4 v151, v[56:59], s[42:43]
	v_lshlrev_b32_e32 v180, 16, v216
	v_and_b32_e32 v181, 0xffff0000, v216
	v_lshlrev_b32_e32 v182, 16, v217
	v_and_b32_e32 v183, 0xffff0000, v217
	v_lshlrev_b32_e32 v184, 16, v218
	v_and_b32_e32 v185, 0xffff0000, v218
	v_lshlrev_b32_e32 v186, 16, v219
	v_and_b32_e32 v187, 0xffff0000, v219
	v_pk_fma_f32 v[52:53], v[52:53], v[204:205], v[180:181]
	v_pk_fma_f32 v[54:55], v[54:55], v[206:207], v[182:183]
	v_pk_fma_f32 v[48:49], v[48:49], v[208:209], v[184:185]
	v_pk_fma_f32 v[50:51], v[50:51], v[210:211], v[186:187]
	v_cvt_pk_bf16_f32 v51, v50, v51
	v_cvt_pk_bf16_f32 v50, v48, v49
	v_cvt_pk_bf16_f32 v49, v54, v55
	v_cvt_pk_bf16_f32 v48, v52, v53
	v_add_u32_e32 v151, 0x80000, v148
	global_store_dwordx4 v151, v[48:51], s[42:43] offset:256
	v_lshlrev_b32_e32 v180, 16, v220
	v_and_b32_e32 v181, 0xffff0000, v220
	v_lshlrev_b32_e32 v182, 16, v221
	v_and_b32_e32 v183, 0xffff0000, v221
	v_lshlrev_b32_e32 v184, 16, v222
	v_and_b32_e32 v185, 0xffff0000, v222
	v_lshlrev_b32_e32 v186, 16, v223
	v_and_b32_e32 v187, 0xffff0000, v223
	v_pk_fma_f32 v[44:45], v[44:45], v[196:197], v[180:181]
	v_pk_fma_f32 v[46:47], v[46:47], v[198:199], v[182:183]
	v_pk_fma_f32 v[40:41], v[40:41], v[200:201], v[184:185]
	v_pk_fma_f32 v[42:43], v[42:43], v[202:203], v[186:187]
	v_cvt_pk_bf16_f32 v43, v42, v43
	v_cvt_pk_bf16_f32 v42, v40, v41
	v_cvt_pk_bf16_f32 v41, v46, v47
	v_cvt_pk_bf16_f32 v40, v44, v45
	v_add_u32_e32 v151, 0x90000, v148
	global_store_dwordx4 v151, v[40:43], s[42:43]
	v_lshlrev_b32_e32 v180, 16, v224
	v_and_b32_e32 v181, 0xffff0000, v224
	v_lshlrev_b32_e32 v182, 16, v225
	v_and_b32_e32 v183, 0xffff0000, v225
	v_lshlrev_b32_e32 v184, 16, v226
	v_and_b32_e32 v185, 0xffff0000, v226
	v_lshlrev_b32_e32 v186, 16, v227
	v_and_b32_e32 v187, 0xffff0000, v227
	v_pk_fma_f32 v[36:37], v[36:37], v[204:205], v[180:181]
	v_pk_fma_f32 v[38:39], v[38:39], v[206:207], v[182:183]
	v_pk_fma_f32 v[32:33], v[32:33], v[208:209], v[184:185]
	v_pk_fma_f32 v[34:35], v[34:35], v[210:211], v[186:187]
	v_cvt_pk_bf16_f32 v35, v34, v35
	v_cvt_pk_bf16_f32 v34, v32, v33
	v_cvt_pk_bf16_f32 v33, v38, v39
	v_cvt_pk_bf16_f32 v32, v36, v37
	v_add_u32_e32 v151, 0x90000, v148
	global_store_dwordx4 v151, v[32:35], s[42:43] offset:256
	v_lshlrev_b32_e32 v180, 16, v164
	v_and_b32_e32 v181, 0xffff0000, v164
	v_lshlrev_b32_e32 v182, 16, v165
	v_and_b32_e32 v183, 0xffff0000, v165
	v_lshlrev_b32_e32 v184, 16, v166
	v_and_b32_e32 v185, 0xffff0000, v166
	v_lshlrev_b32_e32 v186, 16, v167
	v_and_b32_e32 v187, 0xffff0000, v167
	v_pk_fma_f32 v[28:29], v[28:29], v[196:197], v[180:181]
	v_pk_fma_f32 v[30:31], v[30:31], v[198:199], v[182:183]
	v_pk_fma_f32 v[24:25], v[24:25], v[200:201], v[184:185]
	v_pk_fma_f32 v[26:27], v[26:27], v[202:203], v[186:187]
	v_cvt_pk_bf16_f32 v27, v26, v27
	v_cvt_pk_bf16_f32 v26, v24, v25
	v_cvt_pk_bf16_f32 v25, v30, v31
	v_cvt_pk_bf16_f32 v24, v28, v29
	v_add_u32_e32 v151, 0xa0000, v148
	global_store_dwordx4 v151, v[24:27], s[42:43]
	v_lshlrev_b32_e32 v180, 16, v168
	v_and_b32_e32 v181, 0xffff0000, v168
	v_lshlrev_b32_e32 v182, 16, v169
	v_and_b32_e32 v183, 0xffff0000, v169
	v_lshlrev_b32_e32 v184, 16, v170
	v_and_b32_e32 v185, 0xffff0000, v170
	v_lshlrev_b32_e32 v186, 16, v171
	v_and_b32_e32 v187, 0xffff0000, v171
	v_pk_fma_f32 v[20:21], v[20:21], v[204:205], v[180:181]
	v_pk_fma_f32 v[22:23], v[22:23], v[206:207], v[182:183]
	v_pk_fma_f32 v[16:17], v[16:17], v[208:209], v[184:185]
	v_pk_fma_f32 v[18:19], v[18:19], v[210:211], v[186:187]
	v_cvt_pk_bf16_f32 v19, v18, v19
	v_cvt_pk_bf16_f32 v18, v16, v17
	v_cvt_pk_bf16_f32 v17, v22, v23
	v_cvt_pk_bf16_f32 v16, v20, v21
	v_add_u32_e32 v151, 0xa0000, v148
	global_store_dwordx4 v151, v[16:19], s[42:43] offset:256
	v_lshlrev_b32_e32 v180, 16, v172
	v_and_b32_e32 v181, 0xffff0000, v172
	v_lshlrev_b32_e32 v182, 16, v173
	v_and_b32_e32 v183, 0xffff0000, v173
	v_lshlrev_b32_e32 v184, 16, v174
	v_and_b32_e32 v185, 0xffff0000, v174
	v_lshlrev_b32_e32 v186, 16, v175
	v_and_b32_e32 v187, 0xffff0000, v175
	v_pk_fma_f32 v[12:13], v[12:13], v[196:197], v[180:181]
	v_pk_fma_f32 v[14:15], v[14:15], v[198:199], v[182:183]
	v_pk_fma_f32 v[8:9], v[8:9], v[200:201], v[184:185]
	v_pk_fma_f32 v[10:11], v[10:11], v[202:203], v[186:187]
	v_cvt_pk_bf16_f32 v11, v10, v11
	v_cvt_pk_bf16_f32 v10, v8, v9
	v_cvt_pk_bf16_f32 v9, v14, v15
	v_cvt_pk_bf16_f32 v8, v12, v13
	v_add_u32_e32 v151, 0xb0000, v148
	global_store_dwordx4 v151, v[8:11], s[42:43]
	v_lshlrev_b32_e32 v180, 16, v176
	v_and_b32_e32 v181, 0xffff0000, v176
	v_lshlrev_b32_e32 v182, 16, v177
	v_and_b32_e32 v183, 0xffff0000, v177
	v_lshlrev_b32_e32 v184, 16, v178
	v_and_b32_e32 v185, 0xffff0000, v178
	v_lshlrev_b32_e32 v186, 16, v179
	v_and_b32_e32 v187, 0xffff0000, v179
	v_pk_fma_f32 v[4:5], v[4:5], v[204:205], v[180:181]
	v_pk_fma_f32 v[6:7], v[6:7], v[206:207], v[182:183]
	v_pk_fma_f32 v[0:1], v[0:1], v[208:209], v[184:185]
	v_pk_fma_f32 v[2:3], v[2:3], v[210:211], v[186:187]
	v_cvt_pk_bf16_f32 v3, v2, v3
	v_cvt_pk_bf16_f32 v2, v0, v1
	v_cvt_pk_bf16_f32 v1, v6, v7
	v_cvt_pk_bf16_f32 v0, v4, v5
	v_add_u32_e32 v151, 0xb0000, v148
	global_store_dwordx4 v151, v[0:3], s[42:43] offset:256
.Lepi_g0done_mlpout1:
	s_mov_b32 s33, s10
	s_mov_b32 s24, s14
	s_mov_b64 s[30:31], s[18:19]
	s_mov_b64 s[26:27], s[16:17]
	s_and_b64 vcc, exec, s[0:1]
	s_cbranch_vccz .LBB0_1430
	s_waitcnt vmcnt(0)
	s_cmpk_gt_u32 s12, 0xff
	s_cbranch_scc1 .LBB0_1437
	s_barrier
